# GEMM main loops: per-segment s_setprio flips removed (A/B against the trimmed loader version)
# speedup vs baseline: 1.0156x; 1.0156x over previous
;     __device__ __forceinline__ void prep(int pm, int par, LAS unsigned char* lds) const { if (fold) prep_rowstats(stat, pm, par, lds); }
;     __device__ __forceinline__ void prep(int pm, int par, LAS unsigned char* lds) const { if (!ident) prep_rowstats(stat, pm, par, lds); }
;     __device__ __forceinline__ void prep(int pm, int par, LAS unsigned char* lds) const { prep_rowstats(stat, pm, par, lds); }
; #define G_STAGE(bufoff, gbase) do { _Pragma("unroll") for (int _i = 0; _i < 2; ++_i) \
;         __builtin_amdgcn_global_load_lds((const unsigned*)((const char*)(gbase) + voff[_i]), (LAS unsigned*)(lds + (bufoff) + ldsw + _i * 8192), 16, 0, 0); } while (0)
; #define G_LDA(dst, b, h) do { _Pragma("unroll") for (int m = 0; m < 4; ++m) _Pragma("unroll") for (int k = 0; k < 2; ++k) dst[m][k] = *(const LAS bf16x8*)(lds + G_SA(b, h) + aoff + m * 2048 + k * 1024); } while (0)
; #define G_LDB(dst, b, h) do { _Pragma("unroll") for (int n = 0; n < 2; ++n) _Pragma("unroll") for (int k = 0; k < 2; ++k) dst[n][k] = *(const LAS bf16x8*)(lds + G_SB(b, h) + boff + n * 2048 + k * 1024); } while (0)
; #define G_WAIT_V(n) asm volatile("s_waitcnt vmcnt(" #n ")" ::: "memory")
; #define G_WAIT_L(n) asm volatile("s_waitcnt lgkmcnt(" #n ")" ::: "memory")
; template <class Epi>
; __device__ __forceinline__ void gemm_phase(LAS unsigned char* lds, const bf16_t* Ag, const bf16_t* Btg, const int K, const int nM, const int nN, const Epi& E) {
;     ...
;         for (int t = 0; t < nt; t += 2) {
;             const bool last = (t == nt - 2);
;             const char* a1 = cA + (size_t)(t + 1) * kstep;
;             const char* a2 = last ? nA : cA + (size_t)(t + 2) * kstep; const char* b2 = last ? nB : cB + (size_t)(t + 2) * kstep;
;             const char* a3 = a2 + kstep; const char* b3 = b2 + kstep;
;             if (last && has_next && pmn != pm) E.prep(pmn, par ^ 1, lds);
;             G_LDB(B0, 0, 0); G_SCHED; G_LDA(At, 0, 0); G_STAGE(G_SA(1, 1), a1 + hstep);
;             G_WAIT_L(8); G_BAR; G_WAIT_L(0); G_MMA(0, 0, At, B0); G_BAR; G_SCHED;
;             G_LDB(B1, 0, 1); G_STAGE(G_SB(0, 0), b2);
;             G_BAR; G_WAIT_L(0); G_MMA(0, 1, At, B1); G_BAR;
;             G_LDA(At, 0, 1); G_STAGE(G_SA(0, 0), a2);
;             G_BAR; G_WAIT_L(0); G_MMA(1, 0, At, B0); G_BAR; G_SCHED;
;             G_STAGE(G_SB(0, 1), b2 + hstep);
;             G_WAIT_V(6); G_BAR; G_MMA(1, 1, At, B1); G_BAR;
.LBB0_78:
	s_add_u32 s12, s50, 0xfffc0080
	s_addc_u32 s26, s51, -1
	s_and_b64 s[52:53], s[52:53], exec
	s_cselect_b32 s55, s26, s43
	s_cselect_b32 s54, s12, s42
	s_cselect_b32 s53, s72, s15
	s_cselect_b32 s52, s71, s69
	ds_read_b128 v[124:127], v217
	ds_read_b128 v[128:131], v217 offset:1024
	ds_read_b128 v[132:135], v217 offset:2048
	ds_read_b128 v[136:139], v217 offset:3072
	s_add_i32 m0, s58, 0xc000
	ds_read_b128 v[140:143], v186
	ds_read_b128 v[148:151], v186 offset:1024
	ds_read_b128 v[152:155], v186 offset:2048
	ds_read_b128 v[156:159], v186 offset:3072
	ds_read_b128 v[188:191], v186 offset:4096
	ds_read_b128 v[192:195], v186 offset:5120
	ds_read_b128 v[222:225], v186 offset:6144
	global_load_lds_dwordx4 v170, s[50:51]
	s_add_i32 m0, s58, 0xe000
	ds_read_b128 v[226:229], v186 offset:7168
	global_load_lds_dwordx4 v168, s[50:51]
	s_waitcnt lgkmcnt(8)
	s_barrier
	s_waitcnt lgkmcnt(0)
	s_waitcnt lgkmcnt(0)
	v_mfma_f32_16x16x32_bf16 v[164:167], v[124:127], v[140:143], v[164:167]
	v_mfma_f32_16x16x32_bf16 v[160:163], v[132:135], v[140:143], v[160:163]
	v_mfma_f32_16x16x32_bf16 v[116:119], v[124:127], v[152:155], v[116:119]
	v_mfma_f32_16x16x32_bf16 v[112:115], v[132:135], v[152:155], v[112:115]
	v_mfma_f32_16x16x32_bf16 v[100:103], v[124:127], v[188:191], v[100:103]
	v_mfma_f32_16x16x32_bf16 v[96:99], v[132:135], v[188:191], v[96:99]
	v_mfma_f32_16x16x32_bf16 v[84:87], v[124:127], v[222:225], v[84:87]
	v_mfma_f32_16x16x32_bf16 v[80:83], v[132:135], v[222:225], v[80:83]
	v_mfma_f32_16x16x32_bf16 v[164:167], v[128:131], v[148:151], v[164:167]
	v_mfma_f32_16x16x32_bf16 v[160:163], v[136:139], v[148:151], v[160:163]
	v_mfma_f32_16x16x32_bf16 v[116:119], v[128:131], v[156:159], v[116:119]
	v_mfma_f32_16x16x32_bf16 v[112:115], v[136:139], v[156:159], v[112:115]
	v_mfma_f32_16x16x32_bf16 v[100:103], v[128:131], v[192:195], v[100:103]
	v_mfma_f32_16x16x32_bf16 v[96:99], v[136:139], v[192:195], v[96:99]
	v_mfma_f32_16x16x32_bf16 v[84:87], v[128:131], v[226:229], v[84:87]
	v_mfma_f32_16x16x32_bf16 v[80:83], v[136:139], v[226:229], v[80:83]
	s_barrier
	ds_read_b128 v[230:233], v217 offset:16384
	ds_read_b128 v[234:237], v217 offset:17408
	s_add_i32 m0, s57, 0x10000
	ds_read_b128 v[238:241], v217 offset:18432
	global_load_lds_dwordx4 v0, s[52:53]
	s_add_i32 m0, s57, 0x12000
	ds_read_b128 v[242:245], v217 offset:19456
	global_load_lds_dwordx4 v2, s[52:53]
	s_barrier
	s_waitcnt lgkmcnt(0)
	s_waitcnt lgkmcnt(0)
	v_mfma_f32_16x16x32_bf16 v[144:147], v[230:233], v[140:143], v[144:147]
	v_mfma_f32_16x16x32_bf16 v[120:123], v[238:241], v[140:143], v[120:123]
	v_mfma_f32_16x16x32_bf16 v[108:111], v[230:233], v[152:155], v[108:111]
	v_mfma_f32_16x16x32_bf16 v[104:107], v[238:241], v[152:155], v[104:107]
	v_mfma_f32_16x16x32_bf16 v[92:95], v[230:233], v[188:191], v[92:95]
	v_mfma_f32_16x16x32_bf16 v[88:91], v[238:241], v[188:191], v[88:91]
	v_mfma_f32_16x16x32_bf16 v[76:79], v[230:233], v[222:225], v[76:79]
	v_mfma_f32_16x16x32_bf16 v[72:75], v[238:241], v[222:225], v[72:75]
	v_mfma_f32_16x16x32_bf16 v[144:147], v[234:237], v[148:151], v[144:147]
	v_mfma_f32_16x16x32_bf16 v[120:123], v[242:245], v[148:151], v[120:123]
	v_mfma_f32_16x16x32_bf16 v[108:111], v[234:237], v[156:159], v[108:111]
	v_mfma_f32_16x16x32_bf16 v[104:107], v[242:245], v[156:159], v[104:107]
	v_mfma_f32_16x16x32_bf16 v[92:95], v[234:237], v[192:195], v[92:95]
	v_mfma_f32_16x16x32_bf16 v[88:91], v[242:245], v[192:195], v[88:91]
	v_mfma_f32_16x16x32_bf16 v[76:79], v[234:237], v[226:229], v[76:79]
	v_mfma_f32_16x16x32_bf16 v[72:75], v[242:245], v[226:229], v[72:75]
	s_mov_b32 m0, s58
	s_barrier
	ds_read_b128 v[140:143], v186 offset:16384
	ds_read_b128 v[148:151], v186 offset:17408
	ds_read_b128 v[152:155], v186 offset:18432
	ds_read_b128 v[156:159], v186 offset:19456
	ds_read_b128 v[188:191], v186 offset:20480
	ds_read_b128 v[192:195], v186 offset:21504
	ds_read_b128 v[222:225], v186 offset:22528
	global_load_lds_dwordx4 v0, s[54:55]
	s_mov_b32 m0, s59
	ds_read_b128 v[226:229], v186 offset:23552
	global_load_lds_dwordx4 v2, s[54:55]
	s_barrier
	s_waitcnt lgkmcnt(0)
	s_waitcnt lgkmcnt(0)
	v_mfma_f32_16x16x32_bf16 v[60:63], v[124:127], v[140:143], v[60:63]
	v_mfma_f32_16x16x32_bf16 v[56:59], v[132:135], v[140:143], v[56:59]
	v_mfma_f32_16x16x32_bf16 v[44:47], v[124:127], v[152:155], v[44:47]
	v_mfma_f32_16x16x32_bf16 v[40:43], v[132:135], v[152:155], v[40:43]
	v_mfma_f32_16x16x32_bf16 v[28:31], v[124:127], v[188:191], v[28:31]
	v_mfma_f32_16x16x32_bf16 v[24:27], v[132:135], v[188:191], v[24:27]
	v_mfma_f32_16x16x32_bf16 v[12:15], v[124:127], v[222:225], v[12:15]
	v_mfma_f32_16x16x32_bf16 v[8:11], v[132:135], v[222:225], v[8:11]
	v_mfma_f32_16x16x32_bf16 v[60:63], v[128:131], v[148:151], v[60:63]
	v_mfma_f32_16x16x32_bf16 v[56:59], v[136:139], v[148:151], v[56:59]
	v_mfma_f32_16x16x32_bf16 v[44:47], v[128:131], v[156:159], v[44:47]
	v_mfma_f32_16x16x32_bf16 v[40:43], v[136:139], v[156:159], v[40:43]
	v_mfma_f32_16x16x32_bf16 v[28:31], v[128:131], v[192:195], v[28:31]
	v_mfma_f32_16x16x32_bf16 v[24:27], v[136:139], v[192:195], v[24:27]
	v_mfma_f32_16x16x32_bf16 v[12:15], v[128:131], v[226:229], v[12:15]
	v_mfma_f32_16x16x32_bf16 v[8:11], v[136:139], v[226:229], v[8:11]
	s_barrier
	s_add_u32 s74, s52, 0x40000
	s_addc_u32 s75, s53, 0
	s_add_i32 m0, s57, 0x14000
	s_nop 0
	global_load_lds_dwordx4 v0, s[74:75]
	s_add_i32 m0, s57, 0x16000
	s_nop 0
	global_load_lds_dwordx4 v2, s[74:75]
	s_waitcnt vmcnt(6)
	s_barrier
; #define G_STAGE(bufoff, gbase) do { _Pragma("unroll") for (int _i = 0; _i < 2; ++_i) \
;         __builtin_amdgcn_global_load_lds((const unsigned*)((const char*)(gbase) + voff[_i]), (LAS unsigned*)(lds + (bufoff) + ldsw + _i * 8192), 16, 0, 0); } while (0)
; #define G_LDA(dst, b, h) do { _Pragma("unroll") for (int m = 0; m < 4; ++m) _Pragma("unroll") for (int k = 0; k < 2; ++k) dst[m][k] = *(const LAS bf16x8*)(lds + G_SA(b, h) + aoff + m * 2048 + k * 1024); } while (0)
; #define G_LDB(dst, b, h) do { _Pragma("unroll") for (int n = 0; n < 2; ++n) _Pragma("unroll") for (int k = 0; k < 2; ++k) dst[n][k] = *(const LAS bf16x8*)(lds + G_SB(b, h) + boff + n * 2048 + k * 1024); } while (0)
; #define G_MMA(ai, bj, At, Bt) do { __builtin_amdgcn_s_setprio(1); _Pragma("unroll") for (int m = 0; m < 4; ++m) _Pragma("unroll") for (int n = 0; n < 2; ++n) _Pragma("unroll") for (int k = 0; k < 2; ++k) \
;         acc[ai][bj][m][n] = MFMA16(Bt[n][k], At[m][k], acc[ai][bj][m][n]); __builtin_amdgcn_s_setprio(0); } while (0)
; #define G_WAIT_V(n) asm volatile("s_waitcnt vmcnt(" #n ")" ::: "memory")
; #define G_WAIT_L(n) asm volatile("s_waitcnt lgkmcnt(" #n ")" ::: "memory")
; #define G_BAR __builtin_amdgcn_s_barrier()
; #define G_SCHED __builtin_amdgcn_sched_barrier(0)
; template <class Epi>
; __device__ __forceinline__ void gemm_phase(LAS unsigned char* lds, const bf16_t* Ag, const bf16_t* Btg, const int K, const int nM, const int nN, const Epi& E) {
;     ...
;             G_WAIT_V(6); G_BAR; G_MMA(1, 1, At, B1); G_BAR;
;             G_LDB(B0, 1, 0); G_SCHED; G_LDA(At, 1, 0); G_STAGE(G_SA(0, 1), a2 + hstep);
;             G_WAIT_L(8); G_BAR; G_WAIT_L(0); G_MMA(0, 0, At, B0); G_BAR; G_SCHED;
;             G_LDB(B1, 1, 1); G_STAGE(G_SB(1, 0), b3);
	v_mfma_f32_16x16x32_bf16 v[68:71], v[230:233], v[140:143], v[68:71]
	v_mfma_f32_16x16x32_bf16 v[64:67], v[238:241], v[140:143], v[64:67]
	v_mfma_f32_16x16x32_bf16 v[52:55], v[230:233], v[152:155], v[52:55]
	v_mfma_f32_16x16x32_bf16 v[48:51], v[238:241], v[152:155], v[48:51]
	v_mfma_f32_16x16x32_bf16 v[36:39], v[230:233], v[188:191], v[36:39]
	v_mfma_f32_16x16x32_bf16 v[32:35], v[238:241], v[188:191], v[32:35]
	v_mfma_f32_16x16x32_bf16 v[20:23], v[230:233], v[222:225], v[20:23]
	v_mfma_f32_16x16x32_bf16 v[16:19], v[238:241], v[222:225], v[16:19]
	v_mfma_f32_16x16x32_bf16 v[68:71], v[234:237], v[148:151], v[68:71]
	v_mfma_f32_16x16x32_bf16 v[64:67], v[242:245], v[148:151], v[64:67]
	v_mfma_f32_16x16x32_bf16 v[52:55], v[234:237], v[156:159], v[52:55]
	v_mfma_f32_16x16x32_bf16 v[48:51], v[242:245], v[156:159], v[48:51]
	v_mfma_f32_16x16x32_bf16 v[36:39], v[234:237], v[192:195], v[36:39]
	v_mfma_f32_16x16x32_bf16 v[32:35], v[242:245], v[192:195], v[32:35]
	v_mfma_f32_16x16x32_bf16 v[20:23], v[234:237], v[226:229], v[20:23]
	v_mfma_f32_16x16x32_bf16 v[16:19], v[242:245], v[226:229], v[16:19]
	s_barrier
	ds_read_b128 v[124:127], v217 offset:32768
	ds_read_b128 v[128:131], v217 offset:33792
	ds_read_b128 v[132:135], v217 offset:34816
	ds_read_b128 v[136:139], v217 offset:35840
	s_add_u32 s54, s54, 0x40000
	s_addc_u32 s55, s55, 0
	s_mov_b32 m0, s60
	ds_read_b128 v[140:143], v186 offset:32768
	ds_read_b128 v[148:151], v186 offset:33792
	ds_read_b128 v[152:155], v186 offset:34816
	ds_read_b128 v[156:159], v186 offset:35840
	ds_read_b128 v[188:191], v186 offset:36864
	ds_read_b128 v[192:195], v186 offset:37888
	ds_read_b128 v[222:225], v186 offset:38912
	global_load_lds_dwordx4 v0, s[54:55]
	s_mov_b32 m0, s61
	ds_read_b128 v[226:229], v186 offset:39936
	global_load_lds_dwordx4 v2, s[54:55]
	s_waitcnt lgkmcnt(8)
	s_barrier
	s_waitcnt lgkmcnt(0)
	s_waitcnt lgkmcnt(0)
	v_mfma_f32_16x16x32_bf16 v[164:167], v[124:127], v[140:143], v[164:167]
	v_mfma_f32_16x16x32_bf16 v[160:163], v[132:135], v[140:143], v[160:163]
	v_mfma_f32_16x16x32_bf16 v[116:119], v[124:127], v[152:155], v[116:119]
	v_mfma_f32_16x16x32_bf16 v[112:115], v[132:135], v[152:155], v[112:115]
	v_mfma_f32_16x16x32_bf16 v[100:103], v[124:127], v[188:191], v[100:103]
	v_mfma_f32_16x16x32_bf16 v[96:99], v[132:135], v[188:191], v[96:99]
	v_mfma_f32_16x16x32_bf16 v[84:87], v[124:127], v[222:225], v[84:87]
	v_mfma_f32_16x16x32_bf16 v[80:83], v[132:135], v[222:225], v[80:83]
	v_mfma_f32_16x16x32_bf16 v[164:167], v[128:131], v[148:151], v[164:167]
	v_mfma_f32_16x16x32_bf16 v[160:163], v[136:139], v[148:151], v[160:163]
	v_mfma_f32_16x16x32_bf16 v[116:119], v[128:131], v[156:159], v[116:119]
	v_mfma_f32_16x16x32_bf16 v[112:115], v[136:139], v[156:159], v[112:115]
	v_mfma_f32_16x16x32_bf16 v[100:103], v[128:131], v[192:195], v[100:103]
	v_mfma_f32_16x16x32_bf16 v[96:99], v[136:139], v[192:195], v[96:99]
	v_mfma_f32_16x16x32_bf16 v[84:87], v[128:131], v[226:229], v[84:87]
	v_mfma_f32_16x16x32_bf16 v[80:83], v[136:139], v[226:229], v[80:83]
	s_barrier
	s_add_i32 s26, 0, 0x1c000
	s_add_i32 m0, s57, 0x18000
	ds_read_b128 v[230:233], v217 offset:49152
	ds_read_b128 v[234:237], v217 offset:50176
	ds_read_b128 v[238:241], v217 offset:51200
	ds_read_b128 v[242:245], v217 offset:52224
	s_add_u32 s98, s52, 0x80
	s_addc_u32 s99, s53, 0
	global_load_lds_dwordx4 v0, s[98:99]
	s_add_i32 m0, s57, 0x1a000
	s_nop 0
	global_load_lds_dwordx4 v2, s[98:99]
	s_barrier
; #define G_STAGE(bufoff, gbase) do { _Pragma("unroll") for (int _i = 0; _i < 2; ++_i) \
;         __builtin_amdgcn_global_load_lds((const unsigned*)((const char*)(gbase) + voff[_i]), (LAS unsigned*)(lds + (bufoff) + ldsw + _i * 8192), 16, 0, 0); } while (0)
; #define G_LDA(dst, b, h) do { _Pragma("unroll") for (int m = 0; m < 4; ++m) _Pragma("unroll") for (int k = 0; k < 2; ++k) dst[m][k] = *(const LAS bf16x8*)(lds + G_SA(b, h) + aoff + m * 2048 + k * 1024); } while (0)
; #define G_LDB(dst, b, h) do { _Pragma("unroll") for (int n = 0; n < 2; ++n) _Pragma("unroll") for (int k = 0; k < 2; ++k) dst[n][k] = *(const LAS bf16x8*)(lds + G_SB(b, h) + boff + n * 2048 + k * 1024); } while (0)
; #define G_MMA(ai, bj, At, Bt) do { __builtin_amdgcn_s_setprio(1); _Pragma("unroll") for (int m = 0; m < 4; ++m) _Pragma("unroll") for (int n = 0; n < 2; ++n) _Pragma("unroll") for (int k = 0; k < 2; ++k) \
;         acc[ai][bj][m][n] = MFMA16(Bt[n][k], At[m][k], acc[ai][bj][m][n]); __builtin_amdgcn_s_setprio(0); } while (0)
; #define G_WAIT_V(n) asm volatile("s_waitcnt vmcnt(" #n ")" ::: "memory")
; #define G_WAIT_L(n) asm volatile("s_waitcnt lgkmcnt(" #n ")" ::: "memory")
; #define G_BAR __builtin_amdgcn_s_barrier()
; #define G_SCHED __builtin_amdgcn_sched_barrier(0)
; template <class Epi>
; __device__ __forceinline__ void gemm_phase(LAS unsigned char* lds, const bf16_t* Ag, const bf16_t* Btg, const int K, const int nM, const int nN, const Epi& E) {
;     ...
;             G_LDB(B1, 1, 1); G_STAGE(G_SB(1, 0), b3);
;             G_BAR; G_WAIT_L(0); G_MMA(0, 1, At, B1); G_BAR;
;             G_LDA(At, 1, 1); G_STAGE(G_SA(1, 0), a3);
;             G_BAR; G_WAIT_L(0); G_MMA(1, 0, At, B0); G_BAR; G_SCHED;
;             G_STAGE(G_SB(1, 1), b3 + hstep);
;             G_WAIT_V(6); G_BAR; G_MMA(1, 1, At, B1); G_BAR;
	s_waitcnt lgkmcnt(0)
	s_waitcnt lgkmcnt(0)
	v_mfma_f32_16x16x32_bf16 v[144:147], v[230:233], v[140:143], v[144:147]
	v_mfma_f32_16x16x32_bf16 v[120:123], v[238:241], v[140:143], v[120:123]
	v_mfma_f32_16x16x32_bf16 v[108:111], v[230:233], v[152:155], v[108:111]
	v_mfma_f32_16x16x32_bf16 v[104:107], v[238:241], v[152:155], v[104:107]
	v_mfma_f32_16x16x32_bf16 v[92:95], v[230:233], v[188:191], v[92:95]
	v_mfma_f32_16x16x32_bf16 v[88:91], v[238:241], v[188:191], v[88:91]
	v_mfma_f32_16x16x32_bf16 v[76:79], v[230:233], v[222:225], v[76:79]
	v_mfma_f32_16x16x32_bf16 v[72:75], v[238:241], v[222:225], v[72:75]
	v_mfma_f32_16x16x32_bf16 v[144:147], v[234:237], v[148:151], v[144:147]
	v_mfma_f32_16x16x32_bf16 v[120:123], v[242:245], v[148:151], v[120:123]
	v_mfma_f32_16x16x32_bf16 v[108:111], v[234:237], v[156:159], v[108:111]
	v_mfma_f32_16x16x32_bf16 v[104:107], v[242:245], v[156:159], v[104:107]
	v_mfma_f32_16x16x32_bf16 v[92:95], v[234:237], v[192:195], v[92:95]
	v_mfma_f32_16x16x32_bf16 v[88:91], v[242:245], v[192:195], v[88:91]
	v_mfma_f32_16x16x32_bf16 v[76:79], v[234:237], v[226:229], v[76:79]
	v_mfma_f32_16x16x32_bf16 v[72:75], v[242:245], v[226:229], v[72:75]
	s_mov_b32 m0, s62
	s_barrier
	ds_read_b128 v[140:143], v186 offset:49152
	ds_read_b128 v[148:151], v186 offset:50176
	ds_read_b128 v[152:155], v186 offset:51200
	ds_read_b128 v[156:159], v186 offset:52224
	ds_read_b128 v[188:191], v186 offset:53248
	ds_read_b128 v[192:195], v186 offset:54272
	ds_read_b128 v[222:225], v186 offset:55296
	ds_read_b128 v[226:229], v186 offset:56320
	s_add_u32 s98, s54, 0xfffc0080
	s_addc_u32 s99, s55, -1
	global_load_lds_dwordx4 v0, s[98:99]
	s_mov_b32 m0, s63
	s_nop 0
	global_load_lds_dwordx4 v2, s[98:99]
	s_barrier
	s_waitcnt lgkmcnt(0)
	s_waitcnt lgkmcnt(0)
	v_mfma_f32_16x16x32_bf16 v[60:63], v[124:127], v[140:143], v[60:63]
	v_mfma_f32_16x16x32_bf16 v[56:59], v[132:135], v[140:143], v[56:59]
	v_mfma_f32_16x16x32_bf16 v[44:47], v[124:127], v[152:155], v[44:47]
	v_mfma_f32_16x16x32_bf16 v[40:43], v[132:135], v[152:155], v[40:43]
	v_mfma_f32_16x16x32_bf16 v[28:31], v[124:127], v[188:191], v[28:31]
	v_mfma_f32_16x16x32_bf16 v[24:27], v[132:135], v[188:191], v[24:27]
	v_mfma_f32_16x16x32_bf16 v[12:15], v[124:127], v[222:225], v[12:15]
	v_mfma_f32_16x16x32_bf16 v[8:11], v[132:135], v[222:225], v[8:11]
	v_mfma_f32_16x16x32_bf16 v[60:63], v[128:131], v[148:151], v[60:63]
	v_mfma_f32_16x16x32_bf16 v[56:59], v[136:139], v[148:151], v[56:59]
	v_mfma_f32_16x16x32_bf16 v[44:47], v[128:131], v[156:159], v[44:47]
	v_mfma_f32_16x16x32_bf16 v[40:43], v[136:139], v[156:159], v[40:43]
	v_mfma_f32_16x16x32_bf16 v[28:31], v[128:131], v[192:195], v[28:31]
	v_mfma_f32_16x16x32_bf16 v[24:27], v[136:139], v[192:195], v[24:27]
	v_mfma_f32_16x16x32_bf16 v[12:15], v[128:131], v[226:229], v[12:15]
	v_mfma_f32_16x16x32_bf16 v[8:11], v[136:139], v[226:229], v[8:11]
	s_barrier
	s_add_u32 s52, s52, 0x40080
	s_addc_u32 s53, s53, 0
	s_add_i32 s12, s26, s57
	s_add_i32 m0, s57, 0x1c000
	s_nop 0
	global_load_lds_dwordx4 v0, s[52:53]
	s_add_i32 m0, s57, 0x1e000
	s_nop 0
	global_load_lds_dwordx4 v2, s[52:53]
	s_waitcnt vmcnt(6)
	s_barrier
	v_mfma_f32_16x16x32_bf16 v[68:71], v[230:233], v[140:143], v[68:71]
	v_mfma_f32_16x16x32_bf16 v[64:67], v[238:241], v[140:143], v[64:67]
	v_mfma_f32_16x16x32_bf16 v[52:55], v[230:233], v[152:155], v[52:55]
	v_mfma_f32_16x16x32_bf16 v[48:51], v[238:241], v[152:155], v[48:51]
	v_mfma_f32_16x16x32_bf16 v[36:39], v[230:233], v[188:191], v[36:39]
	v_mfma_f32_16x16x32_bf16 v[32:35], v[238:241], v[188:191], v[32:35]
	v_mfma_f32_16x16x32_bf16 v[20:23], v[230:233], v[222:225], v[20:23]
	v_mfma_f32_16x16x32_bf16 v[16:19], v[238:241], v[222:225], v[16:19]
	v_mfma_f32_16x16x32_bf16 v[68:71], v[234:237], v[148:151], v[68:71]
	v_mfma_f32_16x16x32_bf16 v[64:67], v[242:245], v[148:151], v[64:67]
	v_mfma_f32_16x16x32_bf16 v[52:55], v[234:237], v[156:159], v[52:55]
	v_mfma_f32_16x16x32_bf16 v[48:51], v[242:245], v[156:159], v[48:51]
	v_mfma_f32_16x16x32_bf16 v[36:39], v[234:237], v[192:195], v[36:39]
	v_mfma_f32_16x16x32_bf16 v[32:35], v[242:245], v[192:195], v[32:35]
	v_mfma_f32_16x16x32_bf16 v[20:23], v[234:237], v[226:229], v[20:23]
	v_mfma_f32_16x16x32_bf16 v[16:19], v[242:245], v[226:229], v[16:19]
	s_add_i32 s73, s73, 2
	s_add_u32 s71, s71, 0x100
	s_addc_u32 s72, s72, 0
	s_add_u32 s50, s50, 0x100
	s_addc_u32 s51, s51, 0
	s_cmp_gt_u32 s73, 13
	s_barrier
	s_cbranch_scc1 .LBB0_82

;     __device__ __forceinline__ void prep(int pm, int par, LAS unsigned char* lds) const { if (fold) prep_rowstats(stat, pm, par, lds); }
;     __device__ __forceinline__ void prep(int pm, int par, LAS unsigned char* lds) const { if (!ident) prep_rowstats(stat, pm, par, lds); }
;     __device__ __forceinline__ void prep(int pm, int par, LAS unsigned char* lds) const { prep_rowstats(stat, pm, par, lds); }
; #define G_STAGE(bufoff, gbase) do { _Pragma("unroll") for (int _i = 0; _i < 2; ++_i) \
;         __builtin_amdgcn_global_load_lds((const unsigned*)((const char*)(gbase) + voff[_i]), (LAS unsigned*)(lds + (bufoff) + ldsw + _i * 8192), 16, 0, 0); } while (0)
; #define G_LDA(dst, b, h) do { _Pragma("unroll") for (int m = 0; m < 4; ++m) _Pragma("unroll") for (int k = 0; k < 2; ++k) dst[m][k] = *(const LAS bf16x8*)(lds + G_SA(b, h) + aoff + m * 2048 + k * 1024); } while (0)
; #define G_LDB(dst, b, h) do { _Pragma("unroll") for (int n = 0; n < 2; ++n) _Pragma("unroll") for (int k = 0; k < 2; ++k) dst[n][k] = *(const LAS bf16x8*)(lds + G_SB(b, h) + boff + n * 2048 + k * 1024); } while (0)
; #define G_WAIT_V(n) asm volatile("s_waitcnt vmcnt(" #n ")" ::: "memory")
; #define G_WAIT_L(n) asm volatile("s_waitcnt lgkmcnt(" #n ")" ::: "memory")
; template <class Epi>
; __device__ __forceinline__ void gemm_phase(LAS unsigned char* lds, const bf16_t* Ag, const bf16_t* Btg, const int K, const int nM, const int nN, const Epi& E) {
;     ...
;         for (int t = 0; t < nt; t += 2) {
;             const bool last = (t == nt - 2);
;             const char* a1 = cA + (size_t)(t + 1) * kstep;
;             const char* a2 = last ? nA : cA + (size_t)(t + 2) * kstep; const char* b2 = last ? nB : cB + (size_t)(t + 2) * kstep;
;             const char* a3 = a2 + kstep; const char* b3 = b2 + kstep;
;             if (last && has_next && pmn != pm) E.prep(pmn, par ^ 1, lds);
;             G_LDB(B0, 0, 0); G_SCHED; G_LDA(At, 0, 0); G_STAGE(G_SA(1, 1), a1 + hstep);
;             G_WAIT_L(8); G_BAR; G_WAIT_L(0); G_MMA(0, 0, At, B0); G_BAR; G_SCHED;
;             G_LDB(B1, 0, 1); G_STAGE(G_SB(0, 0), b2);
;             G_BAR; G_WAIT_L(0); G_MMA(0, 1, At, B1); G_BAR;
;             G_LDA(At, 0, 1); G_STAGE(G_SA(0, 0), a2);
;             G_BAR; G_WAIT_L(0); G_MMA(1, 0, At, B0); G_BAR; G_SCHED;
;             G_STAGE(G_SB(0, 1), b2 + hstep);
;             G_WAIT_V(6); G_BAR; G_MMA(1, 1, At, B1); G_BAR;
.LBB0_153:
	s_add_u32 s66, s64, 0x100
	s_addc_u32 s67, s65, 0
	s_and_b64 s[68:69], s[68:69], exec
	s_cselect_b32 s71, s67, s55
	s_cselect_b32 s70, s66, s54
	s_cselect_b32 s69, s61, s14
	s_cselect_b32 s68, s57, s15
	ds_read_b128 v[144:147], v217
	ds_read_b128 v[148:151], v217 offset:1024
	ds_read_b128 v[152:155], v217 offset:2048
	ds_read_b128 v[156:159], v217 offset:3072
	s_add_i32 m0, s72, 0xc000
	ds_read_b128 v[160:163], v230
	ds_read_b128 v[164:167], v230 offset:1024
	ds_read_b128 v[168:171], v230 offset:2048
	ds_read_b128 v[172:175], v230 offset:3072
	ds_read_b128 v[180:183], v230 offset:4096
	ds_read_b128 v[184:187], v230 offset:5120
	ds_read_b128 v[188:191], v230 offset:6144
	global_load_lds_dwordx4 v138, s[64:65]
	s_add_i32 m0, s72, 0xe000
	ds_read_b128 v[192:195], v230 offset:7168
	global_load_lds_dwordx4 v136, s[64:65]
	s_waitcnt lgkmcnt(8)
	s_barrier
	s_waitcnt lgkmcnt(0)
	s_waitcnt lgkmcnt(0)
	v_mfma_f32_16x16x32_bf16 v[132:135], v[144:147], v[160:163], v[132:135]
	v_mfma_f32_16x16x32_bf16 v[128:131], v[152:155], v[160:163], v[128:131]
	v_mfma_f32_16x16x32_bf16 v[116:119], v[144:147], v[168:171], v[116:119]
	v_mfma_f32_16x16x32_bf16 v[112:115], v[152:155], v[168:171], v[112:115]
	v_mfma_f32_16x16x32_bf16 v[100:103], v[144:147], v[180:183], v[100:103]
	v_mfma_f32_16x16x32_bf16 v[96:99], v[152:155], v[180:183], v[96:99]
	v_mfma_f32_16x16x32_bf16 v[84:87], v[144:147], v[188:191], v[84:87]
	v_mfma_f32_16x16x32_bf16 v[80:83], v[152:155], v[188:191], v[80:83]
	v_mfma_f32_16x16x32_bf16 v[132:135], v[148:151], v[164:167], v[132:135]
	v_mfma_f32_16x16x32_bf16 v[128:131], v[156:159], v[164:167], v[128:131]
	v_mfma_f32_16x16x32_bf16 v[116:119], v[148:151], v[172:175], v[116:119]
	v_mfma_f32_16x16x32_bf16 v[112:115], v[156:159], v[172:175], v[112:115]
	v_mfma_f32_16x16x32_bf16 v[100:103], v[148:151], v[184:187], v[100:103]
	v_mfma_f32_16x16x32_bf16 v[96:99], v[156:159], v[184:187], v[96:99]
	v_mfma_f32_16x16x32_bf16 v[84:87], v[148:151], v[192:195], v[84:87]
	v_mfma_f32_16x16x32_bf16 v[80:83], v[156:159], v[192:195], v[80:83]
	s_barrier
	s_add_i32 m0, s21, 0x10000
	ds_read_b128 v[232:235], v217 offset:16384
	ds_read_b128 v[236:239], v217 offset:17408
	ds_read_b128 v[240:243], v217 offset:18432
	global_load_lds_dwordx4 v0, s[68:69]
	s_add_i32 m0, s21, 0x12000
	ds_read_b128 v[244:247], v217 offset:19456
	global_load_lds_dwordx4 v2, s[68:69]
	s_barrier
	s_waitcnt lgkmcnt(0)
	s_waitcnt lgkmcnt(0)
	v_mfma_f32_16x16x32_bf16 v[124:127], v[232:235], v[160:163], v[124:127]
	v_mfma_f32_16x16x32_bf16 v[120:123], v[240:243], v[160:163], v[120:123]
	v_mfma_f32_16x16x32_bf16 v[108:111], v[232:235], v[168:171], v[108:111]
	v_mfma_f32_16x16x32_bf16 v[104:107], v[240:243], v[168:171], v[104:107]
	v_mfma_f32_16x16x32_bf16 v[92:95], v[232:235], v[180:183], v[92:95]
	v_mfma_f32_16x16x32_bf16 v[88:91], v[240:243], v[180:183], v[88:91]
	v_mfma_f32_16x16x32_bf16 v[76:79], v[232:235], v[188:191], v[76:79]
	v_mfma_f32_16x16x32_bf16 v[72:75], v[240:243], v[188:191], v[72:75]
	v_mfma_f32_16x16x32_bf16 v[124:127], v[236:239], v[164:167], v[124:127]
	v_mfma_f32_16x16x32_bf16 v[120:123], v[244:247], v[164:167], v[120:123]
	v_mfma_f32_16x16x32_bf16 v[108:111], v[236:239], v[172:175], v[108:111]
	v_mfma_f32_16x16x32_bf16 v[104:107], v[244:247], v[172:175], v[104:107]
	v_mfma_f32_16x16x32_bf16 v[92:95], v[236:239], v[184:187], v[92:95]
	v_mfma_f32_16x16x32_bf16 v[88:91], v[244:247], v[184:187], v[88:91]
	v_mfma_f32_16x16x32_bf16 v[76:79], v[236:239], v[192:195], v[76:79]
	v_mfma_f32_16x16x32_bf16 v[72:75], v[244:247], v[192:195], v[72:75]
	s_mov_b32 m0, s72
	s_barrier
	ds_read_b128 v[160:163], v230 offset:16384
	ds_read_b128 v[164:167], v230 offset:17408
	ds_read_b128 v[168:171], v230 offset:18432
	ds_read_b128 v[172:175], v230 offset:19456
	ds_read_b128 v[180:183], v230 offset:20480
	ds_read_b128 v[184:187], v230 offset:21504
	ds_read_b128 v[188:191], v230 offset:22528
	global_load_lds_dwordx4 v0, s[70:71]
	s_mov_b32 m0, s73
	ds_read_b128 v[192:195], v230 offset:23552
	global_load_lds_dwordx4 v2, s[70:71]
	s_barrier
	s_waitcnt lgkmcnt(0)
	s_waitcnt lgkmcnt(0)
	v_mfma_f32_16x16x32_bf16 v[68:71], v[144:147], v[160:163], v[68:71]
	v_mfma_f32_16x16x32_bf16 v[64:67], v[152:155], v[160:163], v[64:67]
	v_mfma_f32_16x16x32_bf16 v[52:55], v[144:147], v[168:171], v[52:55]
	v_mfma_f32_16x16x32_bf16 v[48:51], v[152:155], v[168:171], v[48:51]
	v_mfma_f32_16x16x32_bf16 v[36:39], v[144:147], v[180:183], v[36:39]
	v_mfma_f32_16x16x32_bf16 v[32:35], v[152:155], v[180:183], v[32:35]
	v_mfma_f32_16x16x32_bf16 v[20:23], v[144:147], v[188:191], v[20:23]
	v_mfma_f32_16x16x32_bf16 v[16:19], v[152:155], v[188:191], v[16:19]
	v_mfma_f32_16x16x32_bf16 v[68:71], v[148:151], v[164:167], v[68:71]
	v_mfma_f32_16x16x32_bf16 v[64:67], v[156:159], v[164:167], v[64:67]
	v_mfma_f32_16x16x32_bf16 v[52:55], v[148:151], v[172:175], v[52:55]
	v_mfma_f32_16x16x32_bf16 v[48:51], v[156:159], v[172:175], v[48:51]
	v_mfma_f32_16x16x32_bf16 v[36:39], v[148:151], v[184:187], v[36:39]
	v_mfma_f32_16x16x32_bf16 v[32:35], v[156:159], v[184:187], v[32:35]
	v_mfma_f32_16x16x32_bf16 v[20:23], v[148:151], v[192:195], v[20:23]
	v_mfma_f32_16x16x32_bf16 v[16:19], v[156:159], v[192:195], v[16:19]
	s_barrier
	s_add_u32 s64, s68, 0x40000
	s_addc_u32 s65, s69, 0
	s_add_i32 m0, s21, 0x14000
	s_nop 0
	global_load_lds_dwordx4 v0, s[64:65]
	s_add_i32 m0, s21, 0x16000
	s_nop 0
	global_load_lds_dwordx4 v2, s[64:65]
	s_waitcnt vmcnt(6)
	s_barrier
; #define G_STAGE(bufoff, gbase) do { _Pragma("unroll") for (int _i = 0; _i < 2; ++_i) \
;         __builtin_amdgcn_global_load_lds((const unsigned*)((const char*)(gbase) + voff[_i]), (LAS unsigned*)(lds + (bufoff) + ldsw + _i * 8192), 16, 0, 0); } while (0)
; #define G_LDA(dst, b, h) do { _Pragma("unroll") for (int m = 0; m < 4; ++m) _Pragma("unroll") for (int k = 0; k < 2; ++k) dst[m][k] = *(const LAS bf16x8*)(lds + G_SA(b, h) + aoff + m * 2048 + k * 1024); } while (0)
; #define G_LDB(dst, b, h) do { _Pragma("unroll") for (int n = 0; n < 2; ++n) _Pragma("unroll") for (int k = 0; k < 2; ++k) dst[n][k] = *(const LAS bf16x8*)(lds + G_SB(b, h) + boff + n * 2048 + k * 1024); } while (0)
; #define G_MMA(ai, bj, At, Bt) do { __builtin_amdgcn_s_setprio(1); _Pragma("unroll") for (int m = 0; m < 4; ++m) _Pragma("unroll") for (int n = 0; n < 2; ++n) _Pragma("unroll") for (int k = 0; k < 2; ++k) \
;         acc[ai][bj][m][n] = MFMA16(Bt[n][k], At[m][k], acc[ai][bj][m][n]); __builtin_amdgcn_s_setprio(0); } while (0)
; #define G_WAIT_V(n) asm volatile("s_waitcnt vmcnt(" #n ")" ::: "memory")
; #define G_WAIT_L(n) asm volatile("s_waitcnt lgkmcnt(" #n ")" ::: "memory")
; #define G_BAR __builtin_amdgcn_s_barrier()
; #define G_SCHED __builtin_amdgcn_sched_barrier(0)
; template <class Epi>
; __device__ __forceinline__ void gemm_phase(LAS unsigned char* lds, const bf16_t* Ag, const bf16_t* Btg, const int K, const int nM, const int nN, const Epi& E) {
;     ...
;             G_WAIT_V(6); G_BAR; G_MMA(1, 1, At, B1); G_BAR;
;             G_LDB(B0, 1, 0); G_SCHED; G_LDA(At, 1, 0); G_STAGE(G_SA(0, 1), a2 + hstep);
;             G_WAIT_L(8); G_BAR; G_WAIT_L(0); G_MMA(0, 0, At, B0); G_BAR; G_SCHED;
;             G_LDB(B1, 1, 1); G_STAGE(G_SB(1, 0), b3);
	v_mfma_f32_16x16x32_bf16 v[60:63], v[232:235], v[160:163], v[60:63]
	v_mfma_f32_16x16x32_bf16 v[56:59], v[240:243], v[160:163], v[56:59]
	v_mfma_f32_16x16x32_bf16 v[44:47], v[232:235], v[168:171], v[44:47]
	v_mfma_f32_16x16x32_bf16 v[40:43], v[240:243], v[168:171], v[40:43]
	v_mfma_f32_16x16x32_bf16 v[28:31], v[232:235], v[180:183], v[28:31]
	v_mfma_f32_16x16x32_bf16 v[24:27], v[240:243], v[180:183], v[24:27]
	v_mfma_f32_16x16x32_bf16 v[12:15], v[232:235], v[188:191], v[12:15]
	v_mfma_f32_16x16x32_bf16 v[8:11], v[240:243], v[188:191], v[8:11]
	v_mfma_f32_16x16x32_bf16 v[60:63], v[236:239], v[164:167], v[60:63]
	v_mfma_f32_16x16x32_bf16 v[56:59], v[244:247], v[164:167], v[56:59]
	v_mfma_f32_16x16x32_bf16 v[44:47], v[236:239], v[172:175], v[44:47]
	v_mfma_f32_16x16x32_bf16 v[40:43], v[244:247], v[172:175], v[40:43]
	v_mfma_f32_16x16x32_bf16 v[28:31], v[236:239], v[184:187], v[28:31]
	v_mfma_f32_16x16x32_bf16 v[24:27], v[244:247], v[184:187], v[24:27]
	v_mfma_f32_16x16x32_bf16 v[12:15], v[236:239], v[192:195], v[12:15]
	v_mfma_f32_16x16x32_bf16 v[8:11], v[244:247], v[192:195], v[8:11]
	s_barrier
	ds_read_b128 v[144:147], v217 offset:32768
	ds_read_b128 v[148:151], v217 offset:33792
	ds_read_b128 v[152:155], v217 offset:34816
	ds_read_b128 v[156:159], v217 offset:35840
	s_add_u32 s64, s70, 0x40000
	s_addc_u32 s65, s71, 0
	s_mov_b32 m0, s74
	ds_read_b128 v[160:163], v230 offset:32768
	ds_read_b128 v[164:167], v230 offset:33792
	ds_read_b128 v[168:171], v230 offset:34816
	ds_read_b128 v[172:175], v230 offset:35840
	ds_read_b128 v[180:183], v230 offset:36864
	ds_read_b128 v[184:187], v230 offset:37888
	ds_read_b128 v[188:191], v230 offset:38912
	global_load_lds_dwordx4 v0, s[64:65]
	s_mov_b32 m0, s75
	ds_read_b128 v[192:195], v230 offset:39936
	global_load_lds_dwordx4 v2, s[64:65]
	s_waitcnt lgkmcnt(8)
	s_barrier
	s_waitcnt lgkmcnt(0)
	s_waitcnt lgkmcnt(0)
	v_mfma_f32_16x16x32_bf16 v[132:135], v[144:147], v[160:163], v[132:135]
	v_mfma_f32_16x16x32_bf16 v[128:131], v[152:155], v[160:163], v[128:131]
	v_mfma_f32_16x16x32_bf16 v[116:119], v[144:147], v[168:171], v[116:119]
	v_mfma_f32_16x16x32_bf16 v[112:115], v[152:155], v[168:171], v[112:115]
	v_mfma_f32_16x16x32_bf16 v[100:103], v[144:147], v[180:183], v[100:103]
	v_mfma_f32_16x16x32_bf16 v[96:99], v[152:155], v[180:183], v[96:99]
	v_mfma_f32_16x16x32_bf16 v[84:87], v[144:147], v[188:191], v[84:87]
	v_mfma_f32_16x16x32_bf16 v[80:83], v[152:155], v[188:191], v[80:83]
	v_mfma_f32_16x16x32_bf16 v[132:135], v[148:151], v[164:167], v[132:135]
	v_mfma_f32_16x16x32_bf16 v[128:131], v[156:159], v[164:167], v[128:131]
	v_mfma_f32_16x16x32_bf16 v[116:119], v[148:151], v[172:175], v[116:119]
	v_mfma_f32_16x16x32_bf16 v[112:115], v[156:159], v[172:175], v[112:115]
	v_mfma_f32_16x16x32_bf16 v[100:103], v[148:151], v[184:187], v[100:103]
	v_mfma_f32_16x16x32_bf16 v[96:99], v[156:159], v[184:187], v[96:99]
	v_mfma_f32_16x16x32_bf16 v[84:87], v[148:151], v[192:195], v[84:87]
	v_mfma_f32_16x16x32_bf16 v[80:83], v[156:159], v[192:195], v[80:83]
	s_barrier
	s_add_i32 s26, 0, 0x1c000
	s_add_i32 m0, s21, 0x18000
	ds_read_b128 v[232:235], v217 offset:49152
	ds_read_b128 v[236:239], v217 offset:50176
	ds_read_b128 v[240:243], v217 offset:51200
	ds_read_b128 v[244:247], v217 offset:52224
	s_add_u32 s98, s68, 0x80
	s_addc_u32 s99, s69, 0
	global_load_lds_dwordx4 v0, s[98:99]
	s_add_i32 m0, s21, 0x1a000
	s_nop 0
	global_load_lds_dwordx4 v2, s[98:99]
	s_barrier
; #define G_STAGE(bufoff, gbase) do { _Pragma("unroll") for (int _i = 0; _i < 2; ++_i) \
;         __builtin_amdgcn_global_load_lds((const unsigned*)((const char*)(gbase) + voff[_i]), (LAS unsigned*)(lds + (bufoff) + ldsw + _i * 8192), 16, 0, 0); } while (0)
; #define G_LDA(dst, b, h) do { _Pragma("unroll") for (int m = 0; m < 4; ++m) _Pragma("unroll") for (int k = 0; k < 2; ++k) dst[m][k] = *(const LAS bf16x8*)(lds + G_SA(b, h) + aoff + m * 2048 + k * 1024); } while (0)
; #define G_LDB(dst, b, h) do { _Pragma("unroll") for (int n = 0; n < 2; ++n) _Pragma("unroll") for (int k = 0; k < 2; ++k) dst[n][k] = *(const LAS bf16x8*)(lds + G_SB(b, h) + boff + n * 2048 + k * 1024); } while (0)
; #define G_MMA(ai, bj, At, Bt) do { __builtin_amdgcn_s_setprio(1); _Pragma("unroll") for (int m = 0; m < 4; ++m) _Pragma("unroll") for (int n = 0; n < 2; ++n) _Pragma("unroll") for (int k = 0; k < 2; ++k) \
;         acc[ai][bj][m][n] = MFMA16(Bt[n][k], At[m][k], acc[ai][bj][m][n]); __builtin_amdgcn_s_setprio(0); } while (0)
; #define G_WAIT_V(n) asm volatile("s_waitcnt vmcnt(" #n ")" ::: "memory")
; #define G_WAIT_L(n) asm volatile("s_waitcnt lgkmcnt(" #n ")" ::: "memory")
; #define G_BAR __builtin_amdgcn_s_barrier()
; #define G_SCHED __builtin_amdgcn_sched_barrier(0)
; template <class Epi>
; __device__ __forceinline__ void gemm_phase(LAS unsigned char* lds, const bf16_t* Ag, const bf16_t* Btg, const int K, const int nM, const int nN, const Epi& E) {
;     ...
;             G_LDB(B1, 1, 1); G_STAGE(G_SB(1, 0), b3);
;             G_BAR; G_WAIT_L(0); G_MMA(0, 1, At, B1); G_BAR;
;             G_LDA(At, 1, 1); G_STAGE(G_SA(1, 0), a3);
;             G_BAR; G_WAIT_L(0); G_MMA(1, 0, At, B0); G_BAR; G_SCHED;
;             G_STAGE(G_SB(1, 1), b3 + hstep);
;             G_WAIT_V(6); G_BAR; G_MMA(1, 1, At, B1); G_BAR;
	s_waitcnt lgkmcnt(0)
	s_waitcnt lgkmcnt(0)
	v_mfma_f32_16x16x32_bf16 v[124:127], v[232:235], v[160:163], v[124:127]
	v_mfma_f32_16x16x32_bf16 v[120:123], v[240:243], v[160:163], v[120:123]
	v_mfma_f32_16x16x32_bf16 v[108:111], v[232:235], v[168:171], v[108:111]
	v_mfma_f32_16x16x32_bf16 v[104:107], v[240:243], v[168:171], v[104:107]
	v_mfma_f32_16x16x32_bf16 v[92:95], v[232:235], v[180:183], v[92:95]
	v_mfma_f32_16x16x32_bf16 v[88:91], v[240:243], v[180:183], v[88:91]
	v_mfma_f32_16x16x32_bf16 v[76:79], v[232:235], v[188:191], v[76:79]
	v_mfma_f32_16x16x32_bf16 v[72:75], v[240:243], v[188:191], v[72:75]
	v_mfma_f32_16x16x32_bf16 v[124:127], v[236:239], v[164:167], v[124:127]
	v_mfma_f32_16x16x32_bf16 v[120:123], v[244:247], v[164:167], v[120:123]
	v_mfma_f32_16x16x32_bf16 v[108:111], v[236:239], v[172:175], v[108:111]
	v_mfma_f32_16x16x32_bf16 v[104:107], v[244:247], v[172:175], v[104:107]
	v_mfma_f32_16x16x32_bf16 v[92:95], v[236:239], v[184:187], v[92:95]
	v_mfma_f32_16x16x32_bf16 v[88:91], v[244:247], v[184:187], v[88:91]
	v_mfma_f32_16x16x32_bf16 v[76:79], v[236:239], v[192:195], v[76:79]
	v_mfma_f32_16x16x32_bf16 v[72:75], v[244:247], v[192:195], v[72:75]
	s_mov_b32 m0, s76
	s_barrier
	ds_read_b128 v[160:163], v230 offset:49152
	ds_read_b128 v[164:167], v230 offset:50176
	ds_read_b128 v[168:171], v230 offset:51200
	ds_read_b128 v[172:175], v230 offset:52224
	ds_read_b128 v[180:183], v230 offset:53248
	ds_read_b128 v[184:187], v230 offset:54272
	ds_read_b128 v[188:191], v230 offset:55296
	ds_read_b128 v[192:195], v230 offset:56320
	s_add_u32 s98, s70, 0x80
	s_addc_u32 s99, s71, 0
	global_load_lds_dwordx4 v0, s[98:99]
	s_mov_b32 m0, s77
	s_nop 0
	global_load_lds_dwordx4 v2, s[98:99]
	s_barrier
	s_waitcnt lgkmcnt(0)
	s_waitcnt lgkmcnt(0)
	v_mfma_f32_16x16x32_bf16 v[68:71], v[144:147], v[160:163], v[68:71]
	v_mfma_f32_16x16x32_bf16 v[64:67], v[152:155], v[160:163], v[64:67]
	v_mfma_f32_16x16x32_bf16 v[52:55], v[144:147], v[168:171], v[52:55]
	v_mfma_f32_16x16x32_bf16 v[48:51], v[152:155], v[168:171], v[48:51]
	v_mfma_f32_16x16x32_bf16 v[36:39], v[144:147], v[180:183], v[36:39]
	v_mfma_f32_16x16x32_bf16 v[32:35], v[152:155], v[180:183], v[32:35]
	v_mfma_f32_16x16x32_bf16 v[20:23], v[144:147], v[188:191], v[20:23]
	v_mfma_f32_16x16x32_bf16 v[16:19], v[152:155], v[188:191], v[16:19]
	v_mfma_f32_16x16x32_bf16 v[68:71], v[148:151], v[164:167], v[68:71]
	v_mfma_f32_16x16x32_bf16 v[64:67], v[156:159], v[164:167], v[64:67]
	v_mfma_f32_16x16x32_bf16 v[52:55], v[148:151], v[172:175], v[52:55]
	v_mfma_f32_16x16x32_bf16 v[48:51], v[156:159], v[172:175], v[48:51]
	v_mfma_f32_16x16x32_bf16 v[36:39], v[148:151], v[184:187], v[36:39]
	v_mfma_f32_16x16x32_bf16 v[32:35], v[156:159], v[184:187], v[32:35]
	v_mfma_f32_16x16x32_bf16 v[20:23], v[148:151], v[192:195], v[20:23]
	v_mfma_f32_16x16x32_bf16 v[16:19], v[156:159], v[192:195], v[16:19]
	s_barrier
	s_add_u32 s64, s68, 0x40080
	s_addc_u32 s65, s69, 0
	s_add_i32 s12, s26, s21
	s_add_i32 m0, s21, 0x1c000
	s_nop 0
	global_load_lds_dwordx4 v0, s[64:65]
	s_add_i32 m0, s21, 0x1e000
	s_nop 0
	global_load_lds_dwordx4 v2, s[64:65]
	s_waitcnt vmcnt(6)
	s_barrier
	v_mfma_f32_16x16x32_bf16 v[60:63], v[232:235], v[160:163], v[60:63]
	v_mfma_f32_16x16x32_bf16 v[56:59], v[240:243], v[160:163], v[56:59]
	v_mfma_f32_16x16x32_bf16 v[44:47], v[232:235], v[168:171], v[44:47]
	v_mfma_f32_16x16x32_bf16 v[40:43], v[240:243], v[168:171], v[40:43]
	v_mfma_f32_16x16x32_bf16 v[28:31], v[232:235], v[180:183], v[28:31]
	v_mfma_f32_16x16x32_bf16 v[24:27], v[240:243], v[180:183], v[24:27]
	v_mfma_f32_16x16x32_bf16 v[12:15], v[232:235], v[188:191], v[12:15]
	v_mfma_f32_16x16x32_bf16 v[8:11], v[240:243], v[188:191], v[8:11]
	v_mfma_f32_16x16x32_bf16 v[60:63], v[236:239], v[164:167], v[60:63]
	v_mfma_f32_16x16x32_bf16 v[56:59], v[244:247], v[164:167], v[56:59]
	v_mfma_f32_16x16x32_bf16 v[44:47], v[236:239], v[172:175], v[44:47]
	v_mfma_f32_16x16x32_bf16 v[40:43], v[244:247], v[172:175], v[40:43]
	v_mfma_f32_16x16x32_bf16 v[28:31], v[236:239], v[184:187], v[28:31]
	v_mfma_f32_16x16x32_bf16 v[24:27], v[244:247], v[184:187], v[24:27]
	v_mfma_f32_16x16x32_bf16 v[12:15], v[236:239], v[192:195], v[12:15]
	v_mfma_f32_16x16x32_bf16 v[8:11], v[244:247], v[192:195], v[8:11]
	s_add_i32 s42, s42, 2
	s_add_u32 s57, s57, 0x100
	s_addc_u32 s61, s61, 0
	s_cmp_gt_u32 s42, 13
	s_mov_b64 s[64:65], s[66:67]
	s_barrier
	s_cbranch_scc1 .LBB0_157

;     __device__ __forceinline__ void prep(int pm, int par, LAS unsigned char* lds) const { if (fold) prep_rowstats(stat, pm, par, lds); }
;     __device__ __forceinline__ void prep(int pm, int par, LAS unsigned char* lds) const { if (!ident) prep_rowstats(stat, pm, par, lds); }
;     __device__ __forceinline__ void prep(int pm, int par, LAS unsigned char* lds) const { prep_rowstats(stat, pm, par, lds); }
; #define G_STAGE(bufoff, gbase) do { _Pragma("unroll") for (int _i = 0; _i < 2; ++_i) \
;         __builtin_amdgcn_global_load_lds((const unsigned*)((const char*)(gbase) + voff[_i]), (LAS unsigned*)(lds + (bufoff) + ldsw + _i * 8192), 16, 0, 0); } while (0)
; #define G_LDA(dst, b, h) do { _Pragma("unroll") for (int m = 0; m < 4; ++m) _Pragma("unroll") for (int k = 0; k < 2; ++k) dst[m][k] = *(const LAS bf16x8*)(lds + G_SA(b, h) + aoff + m * 2048 + k * 1024); } while (0)
; #define G_LDB(dst, b, h) do { _Pragma("unroll") for (int n = 0; n < 2; ++n) _Pragma("unroll") for (int k = 0; k < 2; ++k) dst[n][k] = *(const LAS bf16x8*)(lds + G_SB(b, h) + boff + n * 2048 + k * 1024); } while (0)
; #define G_WAIT_V(n) asm volatile("s_waitcnt vmcnt(" #n ")" ::: "memory")
; #define G_WAIT_L(n) asm volatile("s_waitcnt lgkmcnt(" #n ")" ::: "memory")
; template <class Epi>
; __device__ __forceinline__ void gemm_phase(LAS unsigned char* lds, const bf16_t* Ag, const bf16_t* Btg, const int K, const int nM, const int nN, const Epi& E) {
;     ...
;         for (int t = 0; t < nt; t += 2) {
;             const bool last = (t == nt - 2);
;             const char* a1 = cA + (size_t)(t + 1) * kstep;
;             const char* a2 = last ? nA : cA + (size_t)(t + 2) * kstep; const char* b2 = last ? nB : cB + (size_t)(t + 2) * kstep;
;             const char* a3 = a2 + kstep; const char* b3 = b2 + kstep;
;             if (last && has_next && pmn != pm) E.prep(pmn, par ^ 1, lds);
;             G_LDB(B0, 0, 0); G_SCHED; G_LDA(At, 0, 0); G_STAGE(G_SA(1, 1), a1 + hstep);
;             G_WAIT_L(8); G_BAR; G_WAIT_L(0); G_MMA(0, 0, At, B0); G_BAR; G_SCHED;
;             G_LDB(B1, 0, 1); G_STAGE(G_SB(0, 0), b2);
;             G_BAR; G_WAIT_L(0); G_MMA(0, 1, At, B1); G_BAR;
;             G_LDA(At, 0, 1); G_STAGE(G_SA(0, 0), a2);
;             G_BAR; G_WAIT_L(0); G_MMA(1, 0, At, B0); G_BAR; G_SCHED;
;             G_STAGE(G_SB(0, 1), b2 + hstep);
;             G_WAIT_V(6); G_BAR; G_MMA(1, 1, At, B1); G_BAR;
.LBB0_744:
	s_add_u32 s58, s56, 0x100
	s_addc_u32 s59, s57, 0
	s_and_b64 s[60:61], s[60:61], exec
	s_cselect_b32 s63, s59, s47
	s_cselect_b32 s62, s58, s46
	s_cselect_b32 s61, s78, s15
	s_cselect_b32 s60, s77, s49
	ds_read_b128 v[140:143], v217
	ds_read_b128 v[144:147], v217 offset:1024
	ds_read_b128 v[148:151], v217 offset:2048
	ds_read_b128 v[152:155], v217 offset:3072
	s_add_i32 m0, s66, 0xc000
	ds_read_b128 v[156:159], v174
	ds_read_b128 v[160:163], v174 offset:1024
	ds_read_b128 v[180:183], v174 offset:2048
	ds_read_b128 v[184:187], v174 offset:3072
	ds_read_b128 v[188:191], v174 offset:4096
	ds_read_b128 v[192:195], v174 offset:5120
	ds_read_b128 v[222:225], v174 offset:6144
	global_load_lds_dwordx4 v138, s[56:57]
	s_add_i32 m0, s66, 0xe000
	ds_read_b128 v[226:229], v174 offset:7168
	global_load_lds_dwordx4 v136, s[56:57]
	s_waitcnt lgkmcnt(8)
	s_barrier
	s_waitcnt lgkmcnt(0)
	s_waitcnt lgkmcnt(0)
	v_mfma_f32_16x16x32_bf16 v[132:135], v[140:143], v[156:159], v[132:135]
	v_mfma_f32_16x16x32_bf16 v[128:131], v[148:151], v[156:159], v[128:131]
	v_mfma_f32_16x16x32_bf16 v[116:119], v[140:143], v[180:183], v[116:119]
	v_mfma_f32_16x16x32_bf16 v[112:115], v[148:151], v[180:183], v[112:115]
	v_mfma_f32_16x16x32_bf16 v[100:103], v[140:143], v[188:191], v[100:103]
	v_mfma_f32_16x16x32_bf16 v[96:99], v[148:151], v[188:191], v[96:99]
	v_mfma_f32_16x16x32_bf16 v[84:87], v[140:143], v[222:225], v[84:87]
	v_mfma_f32_16x16x32_bf16 v[80:83], v[148:151], v[222:225], v[80:83]
	v_mfma_f32_16x16x32_bf16 v[132:135], v[144:147], v[160:163], v[132:135]
	v_mfma_f32_16x16x32_bf16 v[128:131], v[152:155], v[160:163], v[128:131]
	v_mfma_f32_16x16x32_bf16 v[116:119], v[144:147], v[184:187], v[116:119]
	v_mfma_f32_16x16x32_bf16 v[112:115], v[152:155], v[184:187], v[112:115]
	v_mfma_f32_16x16x32_bf16 v[100:103], v[144:147], v[192:195], v[100:103]
	v_mfma_f32_16x16x32_bf16 v[96:99], v[152:155], v[192:195], v[96:99]
	v_mfma_f32_16x16x32_bf16 v[84:87], v[144:147], v[226:229], v[84:87]
	v_mfma_f32_16x16x32_bf16 v[80:83], v[152:155], v[226:229], v[80:83]
	s_barrier
	s_add_i32 m0, s65, 0x10000
	ds_read_b128 v[230:233], v217 offset:16384
	ds_read_b128 v[234:237], v217 offset:17408
	ds_read_b128 v[238:241], v217 offset:18432
	global_load_lds_dwordx4 v0, s[60:61]
	s_add_i32 m0, s65, 0x12000
	ds_read_b128 v[242:245], v217 offset:19456
	global_load_lds_dwordx4 v2, s[60:61]
	s_barrier
	s_waitcnt lgkmcnt(0)
	s_waitcnt lgkmcnt(0)
	v_mfma_f32_16x16x32_bf16 v[124:127], v[230:233], v[156:159], v[124:127]
	v_mfma_f32_16x16x32_bf16 v[120:123], v[238:241], v[156:159], v[120:123]
	v_mfma_f32_16x16x32_bf16 v[108:111], v[230:233], v[180:183], v[108:111]
	v_mfma_f32_16x16x32_bf16 v[104:107], v[238:241], v[180:183], v[104:107]
	v_mfma_f32_16x16x32_bf16 v[92:95], v[230:233], v[188:191], v[92:95]
	v_mfma_f32_16x16x32_bf16 v[88:91], v[238:241], v[188:191], v[88:91]
	v_mfma_f32_16x16x32_bf16 v[76:79], v[230:233], v[222:225], v[76:79]
	v_mfma_f32_16x16x32_bf16 v[72:75], v[238:241], v[222:225], v[72:75]
	v_mfma_f32_16x16x32_bf16 v[124:127], v[234:237], v[160:163], v[124:127]
	v_mfma_f32_16x16x32_bf16 v[120:123], v[242:245], v[160:163], v[120:123]
	v_mfma_f32_16x16x32_bf16 v[108:111], v[234:237], v[184:187], v[108:111]
	v_mfma_f32_16x16x32_bf16 v[104:107], v[242:245], v[184:187], v[104:107]
	v_mfma_f32_16x16x32_bf16 v[92:95], v[234:237], v[192:195], v[92:95]
	v_mfma_f32_16x16x32_bf16 v[88:91], v[242:245], v[192:195], v[88:91]
	v_mfma_f32_16x16x32_bf16 v[76:79], v[234:237], v[226:229], v[76:79]
	v_mfma_f32_16x16x32_bf16 v[72:75], v[242:245], v[226:229], v[72:75]
	s_mov_b32 m0, s66
	s_barrier
	ds_read_b128 v[156:159], v174 offset:16384
	ds_read_b128 v[160:163], v174 offset:17408
	ds_read_b128 v[180:183], v174 offset:18432
	ds_read_b128 v[184:187], v174 offset:19456
	ds_read_b128 v[188:191], v174 offset:20480
	ds_read_b128 v[192:195], v174 offset:21504
	ds_read_b128 v[222:225], v174 offset:22528
	global_load_lds_dwordx4 v0, s[62:63]
	s_mov_b32 m0, s67
	ds_read_b128 v[226:229], v174 offset:23552
	global_load_lds_dwordx4 v2, s[62:63]
	s_barrier
	s_waitcnt lgkmcnt(0)
	s_waitcnt lgkmcnt(0)
	v_mfma_f32_16x16x32_bf16 v[68:71], v[140:143], v[156:159], v[68:71]
	v_mfma_f32_16x16x32_bf16 v[64:67], v[148:151], v[156:159], v[64:67]
	v_mfma_f32_16x16x32_bf16 v[52:55], v[140:143], v[180:183], v[52:55]
	v_mfma_f32_16x16x32_bf16 v[48:51], v[148:151], v[180:183], v[48:51]
	v_mfma_f32_16x16x32_bf16 v[36:39], v[140:143], v[188:191], v[36:39]
	v_mfma_f32_16x16x32_bf16 v[32:35], v[148:151], v[188:191], v[32:35]
	v_mfma_f32_16x16x32_bf16 v[20:23], v[140:143], v[222:225], v[20:23]
	v_mfma_f32_16x16x32_bf16 v[16:19], v[148:151], v[222:225], v[16:19]
	v_mfma_f32_16x16x32_bf16 v[68:71], v[144:147], v[160:163], v[68:71]
	v_mfma_f32_16x16x32_bf16 v[64:67], v[152:155], v[160:163], v[64:67]
	v_mfma_f32_16x16x32_bf16 v[52:55], v[144:147], v[184:187], v[52:55]
	v_mfma_f32_16x16x32_bf16 v[48:51], v[152:155], v[184:187], v[48:51]
	v_mfma_f32_16x16x32_bf16 v[36:39], v[144:147], v[192:195], v[36:39]
	v_mfma_f32_16x16x32_bf16 v[32:35], v[152:155], v[192:195], v[32:35]
	v_mfma_f32_16x16x32_bf16 v[20:23], v[144:147], v[226:229], v[20:23]
	v_mfma_f32_16x16x32_bf16 v[16:19], v[152:155], v[226:229], v[16:19]
	s_barrier
	s_add_u32 s56, s60, 0x100000
	s_addc_u32 s57, s61, 0
	s_add_i32 m0, s65, 0x14000
	s_nop 0
	global_load_lds_dwordx4 v0, s[56:57]
	s_add_i32 m0, s65, 0x16000
	s_nop 0
	global_load_lds_dwordx4 v2, s[56:57]
	s_waitcnt vmcnt(6)
	s_barrier
; #define G_STAGE(bufoff, gbase) do { _Pragma("unroll") for (int _i = 0; _i < 2; ++_i) \
;         __builtin_amdgcn_global_load_lds((const unsigned*)((const char*)(gbase) + voff[_i]), (LAS unsigned*)(lds + (bufoff) + ldsw + _i * 8192), 16, 0, 0); } while (0)
; #define G_LDA(dst, b, h) do { _Pragma("unroll") for (int m = 0; m < 4; ++m) _Pragma("unroll") for (int k = 0; k < 2; ++k) dst[m][k] = *(const LAS bf16x8*)(lds + G_SA(b, h) + aoff + m * 2048 + k * 1024); } while (0)
; #define G_LDB(dst, b, h) do { _Pragma("unroll") for (int n = 0; n < 2; ++n) _Pragma("unroll") for (int k = 0; k < 2; ++k) dst[n][k] = *(const LAS bf16x8*)(lds + G_SB(b, h) + boff + n * 2048 + k * 1024); } while (0)
; #define G_MMA(ai, bj, At, Bt) do { __builtin_amdgcn_s_setprio(1); _Pragma("unroll") for (int m = 0; m < 4; ++m) _Pragma("unroll") for (int n = 0; n < 2; ++n) _Pragma("unroll") for (int k = 0; k < 2; ++k) \
;         acc[ai][bj][m][n] = MFMA16(Bt[n][k], At[m][k], acc[ai][bj][m][n]); __builtin_amdgcn_s_setprio(0); } while (0)
; #define G_WAIT_V(n) asm volatile("s_waitcnt vmcnt(" #n ")" ::: "memory")
; #define G_WAIT_L(n) asm volatile("s_waitcnt lgkmcnt(" #n ")" ::: "memory")
; #define G_BAR __builtin_amdgcn_s_barrier()
; #define G_SCHED __builtin_amdgcn_sched_barrier(0)
; template <class Epi>
; __device__ __forceinline__ void gemm_phase(LAS unsigned char* lds, const bf16_t* Ag, const bf16_t* Btg, const int K, const int nM, const int nN, const Epi& E) {
;     ...
;             G_WAIT_V(6); G_BAR; G_MMA(1, 1, At, B1); G_BAR;
;             G_LDB(B0, 1, 0); G_SCHED; G_LDA(At, 1, 0); G_STAGE(G_SA(0, 1), a2 + hstep);
;             G_WAIT_L(8); G_BAR; G_WAIT_L(0); G_MMA(0, 0, At, B0); G_BAR; G_SCHED;
;             G_LDB(B1, 1, 1); G_STAGE(G_SB(1, 0), b3);
	v_mfma_f32_16x16x32_bf16 v[60:63], v[230:233], v[156:159], v[60:63]
	v_mfma_f32_16x16x32_bf16 v[56:59], v[238:241], v[156:159], v[56:59]
	v_mfma_f32_16x16x32_bf16 v[44:47], v[230:233], v[180:183], v[44:47]
	v_mfma_f32_16x16x32_bf16 v[40:43], v[238:241], v[180:183], v[40:43]
	v_mfma_f32_16x16x32_bf16 v[28:31], v[230:233], v[188:191], v[28:31]
	v_mfma_f32_16x16x32_bf16 v[24:27], v[238:241], v[188:191], v[24:27]
	v_mfma_f32_16x16x32_bf16 v[12:15], v[230:233], v[222:225], v[12:15]
	v_mfma_f32_16x16x32_bf16 v[8:11], v[238:241], v[222:225], v[8:11]
	v_mfma_f32_16x16x32_bf16 v[60:63], v[234:237], v[160:163], v[60:63]
	v_mfma_f32_16x16x32_bf16 v[56:59], v[242:245], v[160:163], v[56:59]
	v_mfma_f32_16x16x32_bf16 v[44:47], v[234:237], v[184:187], v[44:47]
	v_mfma_f32_16x16x32_bf16 v[40:43], v[242:245], v[184:187], v[40:43]
	v_mfma_f32_16x16x32_bf16 v[28:31], v[234:237], v[192:195], v[28:31]
	v_mfma_f32_16x16x32_bf16 v[24:27], v[242:245], v[192:195], v[24:27]
	v_mfma_f32_16x16x32_bf16 v[12:15], v[234:237], v[226:229], v[12:15]
	v_mfma_f32_16x16x32_bf16 v[8:11], v[242:245], v[226:229], v[8:11]
	s_barrier
	ds_read_b128 v[140:143], v217 offset:32768
	ds_read_b128 v[144:147], v217 offset:33792
	ds_read_b128 v[148:151], v217 offset:34816
	ds_read_b128 v[152:155], v217 offset:35840
	s_add_u32 s56, s62, 0x100000
	s_addc_u32 s57, s63, 0
	s_mov_b32 m0, s68
	ds_read_b128 v[156:159], v174 offset:32768
	ds_read_b128 v[160:163], v174 offset:33792
	ds_read_b128 v[180:183], v174 offset:34816
	ds_read_b128 v[184:187], v174 offset:35840
	ds_read_b128 v[188:191], v174 offset:36864
	ds_read_b128 v[192:195], v174 offset:37888
	ds_read_b128 v[222:225], v174 offset:38912
	global_load_lds_dwordx4 v0, s[56:57]
	s_mov_b32 m0, s69
	ds_read_b128 v[226:229], v174 offset:39936
	global_load_lds_dwordx4 v2, s[56:57]
	s_waitcnt lgkmcnt(8)
	s_barrier
	s_waitcnt lgkmcnt(0)
	s_waitcnt lgkmcnt(0)
	v_mfma_f32_16x16x32_bf16 v[132:135], v[140:143], v[156:159], v[132:135]
	v_mfma_f32_16x16x32_bf16 v[128:131], v[148:151], v[156:159], v[128:131]
	v_mfma_f32_16x16x32_bf16 v[116:119], v[140:143], v[180:183], v[116:119]
	v_mfma_f32_16x16x32_bf16 v[112:115], v[148:151], v[180:183], v[112:115]
	v_mfma_f32_16x16x32_bf16 v[100:103], v[140:143], v[188:191], v[100:103]
	v_mfma_f32_16x16x32_bf16 v[96:99], v[148:151], v[188:191], v[96:99]
	v_mfma_f32_16x16x32_bf16 v[84:87], v[140:143], v[222:225], v[84:87]
	v_mfma_f32_16x16x32_bf16 v[80:83], v[148:151], v[222:225], v[80:83]
	v_mfma_f32_16x16x32_bf16 v[132:135], v[144:147], v[160:163], v[132:135]
	v_mfma_f32_16x16x32_bf16 v[128:131], v[152:155], v[160:163], v[128:131]
	v_mfma_f32_16x16x32_bf16 v[116:119], v[144:147], v[184:187], v[116:119]
	v_mfma_f32_16x16x32_bf16 v[112:115], v[152:155], v[184:187], v[112:115]
	v_mfma_f32_16x16x32_bf16 v[100:103], v[144:147], v[192:195], v[100:103]
	v_mfma_f32_16x16x32_bf16 v[96:99], v[152:155], v[192:195], v[96:99]
	v_mfma_f32_16x16x32_bf16 v[84:87], v[144:147], v[226:229], v[84:87]
	v_mfma_f32_16x16x32_bf16 v[80:83], v[152:155], v[226:229], v[80:83]
	s_barrier
	s_add_i32 s26, 0, 0x1c000
	s_add_i32 m0, s65, 0x18000
	ds_read_b128 v[230:233], v217 offset:49152
	ds_read_b128 v[234:237], v217 offset:50176
	ds_read_b128 v[238:241], v217 offset:51200
	ds_read_b128 v[242:245], v217 offset:52224
	s_add_u32 s98, s60, 0x80
	s_addc_u32 s99, s61, 0
	global_load_lds_dwordx4 v0, s[98:99]
	s_add_i32 m0, s65, 0x1a000
	s_nop 0
	global_load_lds_dwordx4 v2, s[98:99]
	s_barrier
; #define G_STAGE(bufoff, gbase) do { _Pragma("unroll") for (int _i = 0; _i < 2; ++_i) \
;         __builtin_amdgcn_global_load_lds((const unsigned*)((const char*)(gbase) + voff[_i]), (LAS unsigned*)(lds + (bufoff) + ldsw + _i * 8192), 16, 0, 0); } while (0)
; #define G_LDA(dst, b, h) do { _Pragma("unroll") for (int m = 0; m < 4; ++m) _Pragma("unroll") for (int k = 0; k < 2; ++k) dst[m][k] = *(const LAS bf16x8*)(lds + G_SA(b, h) + aoff + m * 2048 + k * 1024); } while (0)
; #define G_LDB(dst, b, h) do { _Pragma("unroll") for (int n = 0; n < 2; ++n) _Pragma("unroll") for (int k = 0; k < 2; ++k) dst[n][k] = *(const LAS bf16x8*)(lds + G_SB(b, h) + boff + n * 2048 + k * 1024); } while (0)
; #define G_MMA(ai, bj, At, Bt) do { __builtin_amdgcn_s_setprio(1); _Pragma("unroll") for (int m = 0; m < 4; ++m) _Pragma("unroll") for (int n = 0; n < 2; ++n) _Pragma("unroll") for (int k = 0; k < 2; ++k) \
;         acc[ai][bj][m][n] = MFMA16(Bt[n][k], At[m][k], acc[ai][bj][m][n]); __builtin_amdgcn_s_setprio(0); } while (0)
; #define G_WAIT_V(n) asm volatile("s_waitcnt vmcnt(" #n ")" ::: "memory")
; #define G_WAIT_L(n) asm volatile("s_waitcnt lgkmcnt(" #n ")" ::: "memory")
; #define G_BAR __builtin_amdgcn_s_barrier()
; #define G_SCHED __builtin_amdgcn_sched_barrier(0)
; template <class Epi>
; __device__ __forceinline__ void gemm_phase(LAS unsigned char* lds, const bf16_t* Ag, const bf16_t* Btg, const int K, const int nM, const int nN, const Epi& E) {
;     ...
;             G_LDB(B1, 1, 1); G_STAGE(G_SB(1, 0), b3);
;             G_BAR; G_WAIT_L(0); G_MMA(0, 1, At, B1); G_BAR;
;             G_LDA(At, 1, 1); G_STAGE(G_SA(1, 0), a3);
;             G_BAR; G_WAIT_L(0); G_MMA(1, 0, At, B0); G_BAR; G_SCHED;
;             G_STAGE(G_SB(1, 1), b3 + hstep);
;             G_WAIT_V(6); G_BAR; G_MMA(1, 1, At, B1); G_BAR;
	s_waitcnt lgkmcnt(0)
	s_waitcnt lgkmcnt(0)
	v_mfma_f32_16x16x32_bf16 v[124:127], v[230:233], v[156:159], v[124:127]
	v_mfma_f32_16x16x32_bf16 v[120:123], v[238:241], v[156:159], v[120:123]
	v_mfma_f32_16x16x32_bf16 v[108:111], v[230:233], v[180:183], v[108:111]
	v_mfma_f32_16x16x32_bf16 v[104:107], v[238:241], v[180:183], v[104:107]
	v_mfma_f32_16x16x32_bf16 v[92:95], v[230:233], v[188:191], v[92:95]
	v_mfma_f32_16x16x32_bf16 v[88:91], v[238:241], v[188:191], v[88:91]
	v_mfma_f32_16x16x32_bf16 v[76:79], v[230:233], v[222:225], v[76:79]
	v_mfma_f32_16x16x32_bf16 v[72:75], v[238:241], v[222:225], v[72:75]
	v_mfma_f32_16x16x32_bf16 v[124:127], v[234:237], v[160:163], v[124:127]
	v_mfma_f32_16x16x32_bf16 v[120:123], v[242:245], v[160:163], v[120:123]
	v_mfma_f32_16x16x32_bf16 v[108:111], v[234:237], v[184:187], v[108:111]
	v_mfma_f32_16x16x32_bf16 v[104:107], v[242:245], v[184:187], v[104:107]
	v_mfma_f32_16x16x32_bf16 v[92:95], v[234:237], v[192:195], v[92:95]
	v_mfma_f32_16x16x32_bf16 v[88:91], v[242:245], v[192:195], v[88:91]
	v_mfma_f32_16x16x32_bf16 v[76:79], v[234:237], v[226:229], v[76:79]
	v_mfma_f32_16x16x32_bf16 v[72:75], v[242:245], v[226:229], v[72:75]
	s_mov_b32 m0, s70
	s_barrier
	ds_read_b128 v[156:159], v174 offset:49152
	ds_read_b128 v[160:163], v174 offset:50176
	ds_read_b128 v[180:183], v174 offset:51200
	ds_read_b128 v[184:187], v174 offset:52224
	ds_read_b128 v[188:191], v174 offset:53248
	ds_read_b128 v[192:195], v174 offset:54272
	ds_read_b128 v[222:225], v174 offset:55296
	ds_read_b128 v[226:229], v174 offset:56320
	s_add_u32 s98, s62, 0x80
	s_addc_u32 s99, s63, 0
	global_load_lds_dwordx4 v0, s[98:99]
	s_mov_b32 m0, s71
	s_nop 0
	global_load_lds_dwordx4 v2, s[98:99]
	s_barrier
	s_waitcnt lgkmcnt(0)
	s_waitcnt lgkmcnt(0)
	v_mfma_f32_16x16x32_bf16 v[68:71], v[140:143], v[156:159], v[68:71]
	v_mfma_f32_16x16x32_bf16 v[64:67], v[148:151], v[156:159], v[64:67]
	v_mfma_f32_16x16x32_bf16 v[52:55], v[140:143], v[180:183], v[52:55]
	v_mfma_f32_16x16x32_bf16 v[48:51], v[148:151], v[180:183], v[48:51]
	v_mfma_f32_16x16x32_bf16 v[36:39], v[140:143], v[188:191], v[36:39]
	v_mfma_f32_16x16x32_bf16 v[32:35], v[148:151], v[188:191], v[32:35]
	v_mfma_f32_16x16x32_bf16 v[20:23], v[140:143], v[222:225], v[20:23]
	v_mfma_f32_16x16x32_bf16 v[16:19], v[148:151], v[222:225], v[16:19]
	v_mfma_f32_16x16x32_bf16 v[68:71], v[144:147], v[160:163], v[68:71]
	v_mfma_f32_16x16x32_bf16 v[64:67], v[152:155], v[160:163], v[64:67]
	v_mfma_f32_16x16x32_bf16 v[52:55], v[144:147], v[184:187], v[52:55]
	v_mfma_f32_16x16x32_bf16 v[48:51], v[152:155], v[184:187], v[48:51]
	v_mfma_f32_16x16x32_bf16 v[36:39], v[144:147], v[192:195], v[36:39]
	v_mfma_f32_16x16x32_bf16 v[32:35], v[152:155], v[192:195], v[32:35]
	v_mfma_f32_16x16x32_bf16 v[20:23], v[144:147], v[226:229], v[20:23]
	v_mfma_f32_16x16x32_bf16 v[16:19], v[152:155], v[226:229], v[16:19]
	s_barrier
	s_add_u32 s56, s60, 0x100080
	s_addc_u32 s57, s61, 0
	s_add_i32 s12, s26, s65
	s_add_i32 m0, s65, 0x1c000
	s_nop 0
	global_load_lds_dwordx4 v0, s[56:57]
	s_add_i32 m0, s65, 0x1e000
	s_nop 0
	global_load_lds_dwordx4 v2, s[56:57]
	s_waitcnt vmcnt(6)
	s_barrier
	v_mfma_f32_16x16x32_bf16 v[60:63], v[230:233], v[156:159], v[60:63]
	v_mfma_f32_16x16x32_bf16 v[56:59], v[238:241], v[156:159], v[56:59]
	v_mfma_f32_16x16x32_bf16 v[44:47], v[230:233], v[180:183], v[44:47]
	v_mfma_f32_16x16x32_bf16 v[40:43], v[238:241], v[180:183], v[40:43]
	v_mfma_f32_16x16x32_bf16 v[28:31], v[230:233], v[188:191], v[28:31]
	v_mfma_f32_16x16x32_bf16 v[24:27], v[238:241], v[188:191], v[24:27]
	v_mfma_f32_16x16x32_bf16 v[12:15], v[230:233], v[222:225], v[12:15]
	v_mfma_f32_16x16x32_bf16 v[8:11], v[238:241], v[222:225], v[8:11]
	v_mfma_f32_16x16x32_bf16 v[60:63], v[234:237], v[160:163], v[60:63]
	v_mfma_f32_16x16x32_bf16 v[56:59], v[242:245], v[160:163], v[56:59]
	v_mfma_f32_16x16x32_bf16 v[44:47], v[234:237], v[184:187], v[44:47]
	v_mfma_f32_16x16x32_bf16 v[40:43], v[242:245], v[184:187], v[40:43]
	v_mfma_f32_16x16x32_bf16 v[28:31], v[234:237], v[192:195], v[28:31]
	v_mfma_f32_16x16x32_bf16 v[24:27], v[242:245], v[192:195], v[24:27]
	v_mfma_f32_16x16x32_bf16 v[12:15], v[234:237], v[226:229], v[12:15]
	v_mfma_f32_16x16x32_bf16 v[8:11], v[242:245], v[226:229], v[8:11]
	s_add_i32 s79, s79, 2
	s_add_u32 s77, s77, 0x100
	s_addc_u32 s78, s78, 0
	s_cmp_gt_u32 s79, 61
	s_mov_b64 s[56:57], s[58:59]
	s_barrier
	s_cbranch_scc1 .LBB0_748

;     __device__ __forceinline__ void prep(int pm, int par, LAS unsigned char* lds) const { if (fold) prep_rowstats(stat, pm, par, lds); }
;     __device__ __forceinline__ void prep(int pm, int par, LAS unsigned char* lds) const { if (!ident) prep_rowstats(stat, pm, par, lds); }
;     __device__ __forceinline__ void prep(int pm, int par, LAS unsigned char* lds) const { prep_rowstats(stat, pm, par, lds); }
; #define G_STAGE(bufoff, gbase) do { _Pragma("unroll") for (int _i = 0; _i < 2; ++_i) \
;         __builtin_amdgcn_global_load_lds((const unsigned*)((const char*)(gbase) + voff[_i]), (LAS unsigned*)(lds + (bufoff) + ldsw + _i * 8192), 16, 0, 0); } while (0)
; #define G_LDA(dst, b, h) do { _Pragma("unroll") for (int m = 0; m < 4; ++m) _Pragma("unroll") for (int k = 0; k < 2; ++k) dst[m][k] = *(const LAS bf16x8*)(lds + G_SA(b, h) + aoff + m * 2048 + k * 1024); } while (0)
; #define G_LDB(dst, b, h) do { _Pragma("unroll") for (int n = 0; n < 2; ++n) _Pragma("unroll") for (int k = 0; k < 2; ++k) dst[n][k] = *(const LAS bf16x8*)(lds + G_SB(b, h) + boff + n * 2048 + k * 1024); } while (0)
; #define G_WAIT_V(n) asm volatile("s_waitcnt vmcnt(" #n ")" ::: "memory")
; #define G_WAIT_L(n) asm volatile("s_waitcnt lgkmcnt(" #n ")" ::: "memory")
; template <class Epi>
; __device__ __forceinline__ void gemm_phase(LAS unsigned char* lds, const bf16_t* Ag, const bf16_t* Btg, const int K, const int nM, const int nN, const Epi& E) {
;     ...
;         for (int t = 0; t < nt; t += 2) {
;             const bool last = (t == nt - 2);
;             const char* a1 = cA + (size_t)(t + 1) * kstep;
;             const char* a2 = last ? nA : cA + (size_t)(t + 2) * kstep; const char* b2 = last ? nB : cB + (size_t)(t + 2) * kstep;
;             const char* a3 = a2 + kstep; const char* b3 = b2 + kstep;
;             if (last && has_next && pmn != pm) E.prep(pmn, par ^ 1, lds);
;             G_LDB(B0, 0, 0); G_SCHED; G_LDA(At, 0, 0); G_STAGE(G_SA(1, 1), a1 + hstep);
;             G_WAIT_L(8); G_BAR; G_WAIT_L(0); G_MMA(0, 0, At, B0); G_BAR; G_SCHED;
;             G_LDB(B1, 0, 1); G_STAGE(G_SB(0, 0), b2);
;             G_BAR; G_WAIT_L(0); G_MMA(0, 1, At, B1); G_BAR;
;             G_LDA(At, 0, 1); G_STAGE(G_SA(0, 0), a2);
;             G_BAR; G_WAIT_L(0); G_MMA(1, 0, At, B0); G_BAR; G_SCHED;
;             G_STAGE(G_SB(0, 1), b2 + hstep);
;             G_WAIT_V(6); G_BAR; G_MMA(1, 1, At, B1); G_BAR;
.LBB0_848:
	s_add_u32 s26, s50, 0xfffc0080
	s_addc_u32 s54, s51, -1
	s_and_b64 s[52:53], s[52:53], exec
	s_cselect_b32 s55, s54, s25
	s_cselect_b32 s54, s26, s24
	s_cselect_b32 s53, s71, s14
	s_cselect_b32 s52, s70, s15
	ds_read_b128 v[130:133], v217
	ds_read_b128 v[134:137], v217 offset:1024
	ds_read_b128 v[144:147], v217 offset:2048
	ds_read_b128 v[148:151], v217 offset:3072
	s_add_i32 m0, s60, 0xc000
	ds_read_b128 v[156:159], v222
	ds_read_b128 v[160:163], v222 offset:1024
	ds_read_b128 v[164:167], v222 offset:2048
	ds_read_b128 v[180:183], v222 offset:3072
	ds_read_b128 v[184:187], v222 offset:4096
	ds_read_b128 v[224:227], v222 offset:5120
	ds_read_b128 v[228:231], v222 offset:6144
	global_load_lds_dwordx4 v170, s[50:51]
	s_add_i32 m0, s60, 0xe000
	ds_read_b128 v[232:235], v222 offset:7168
	global_load_lds_dwordx4 v168, s[50:51]
	s_waitcnt lgkmcnt(8)
	s_barrier
	s_waitcnt lgkmcnt(0)
	s_waitcnt lgkmcnt(0)
	v_mfma_f32_16x16x32_bf16 v[152:155], v[130:133], v[156:159], v[152:155]
	v_mfma_f32_16x16x32_bf16 v[138:141], v[144:147], v[156:159], v[140:143]
	v_mfma_f32_16x16x32_bf16 v[116:119], v[130:133], v[164:167], v[116:119]
	v_mfma_f32_16x16x32_bf16 v[112:115], v[144:147], v[164:167], v[112:115]
	v_mfma_f32_16x16x32_bf16 v[100:103], v[130:133], v[184:187], v[100:103]
	v_mfma_f32_16x16x32_bf16 v[96:99], v[144:147], v[184:187], v[96:99]
	v_mfma_f32_16x16x32_bf16 v[84:87], v[130:133], v[228:231], v[84:87]
	v_mfma_f32_16x16x32_bf16 v[80:83], v[144:147], v[228:231], v[80:83]
	v_mfma_f32_16x16x32_bf16 v[152:155], v[134:137], v[160:163], v[152:155]
	v_mfma_f32_16x16x32_bf16 v[138:141], v[148:151], v[160:163], v[138:141]
	v_mfma_f32_16x16x32_bf16 v[116:119], v[134:137], v[180:183], v[116:119]
	v_mfma_f32_16x16x32_bf16 v[112:115], v[148:151], v[180:183], v[112:115]
	v_mfma_f32_16x16x32_bf16 v[100:103], v[134:137], v[224:227], v[100:103]
	v_mfma_f32_16x16x32_bf16 v[96:99], v[148:151], v[224:227], v[96:99]
	v_mfma_f32_16x16x32_bf16 v[84:87], v[134:137], v[232:235], v[84:87]
	v_mfma_f32_16x16x32_bf16 v[80:83], v[148:151], v[232:235], v[80:83]
	s_barrier
	s_add_i32 s73, 0, 0x14000
	s_add_i32 m0, s59, 0x10000
	ds_read_b128 v[236:239], v217 offset:16384
	ds_read_b128 v[240:243], v217 offset:17408
	ds_read_b128 v[244:247], v217 offset:18432
	global_load_lds_dwordx4 v0, s[52:53]
	s_add_i32 m0, s59, 0x12000
	ds_read_b128 v[248:251], v217 offset:19456
	global_load_lds_dwordx4 v2, s[52:53]
	s_barrier
	s_waitcnt lgkmcnt(0)
	s_waitcnt lgkmcnt(0)
	v_mfma_f32_16x16x32_bf16 v[124:127], v[236:239], v[156:159], v[124:127]
	v_mfma_f32_16x16x32_bf16 v[120:123], v[244:247], v[156:159], v[120:123]
	v_mfma_f32_16x16x32_bf16 v[108:111], v[236:239], v[164:167], v[108:111]
	v_mfma_f32_16x16x32_bf16 v[104:107], v[244:247], v[164:167], v[104:107]
	v_mfma_f32_16x16x32_bf16 v[92:95], v[236:239], v[184:187], v[92:95]
	v_mfma_f32_16x16x32_bf16 v[88:91], v[244:247], v[184:187], v[88:91]
	v_mfma_f32_16x16x32_bf16 v[76:79], v[236:239], v[228:231], v[76:79]
	v_mfma_f32_16x16x32_bf16 v[72:75], v[244:247], v[228:231], v[72:75]
	v_mfma_f32_16x16x32_bf16 v[124:127], v[240:243], v[160:163], v[124:127]
	v_mfma_f32_16x16x32_bf16 v[120:123], v[248:251], v[160:163], v[120:123]
	v_mfma_f32_16x16x32_bf16 v[108:111], v[240:243], v[180:183], v[108:111]
	v_mfma_f32_16x16x32_bf16 v[104:107], v[248:251], v[180:183], v[104:107]
	v_mfma_f32_16x16x32_bf16 v[92:95], v[240:243], v[224:227], v[92:95]
	v_mfma_f32_16x16x32_bf16 v[88:91], v[248:251], v[224:227], v[88:91]
	v_mfma_f32_16x16x32_bf16 v[76:79], v[240:243], v[232:235], v[76:79]
	v_mfma_f32_16x16x32_bf16 v[72:75], v[248:251], v[232:235], v[72:75]
	s_mov_b32 m0, s60
	s_add_u32 s76, s54, 0x80
	s_addc_u32 s77, s55, 0
	s_barrier
	ds_read_b128 v[156:159], v222 offset:16384
	ds_read_b128 v[160:163], v222 offset:17408
	ds_read_b128 v[164:167], v222 offset:18432
	ds_read_b128 v[180:183], v222 offset:19456
	ds_read_b128 v[184:187], v222 offset:20480
	ds_read_b128 v[224:227], v222 offset:21504
	ds_read_b128 v[228:231], v222 offset:22528
	ds_read_b128 v[232:235], v222 offset:23552
	global_load_lds_dwordx4 v0, s[54:55]
	s_add_u32 s76, s54, 0x80
	s_mov_b32 m0, s61
	s_addc_u32 s77, s55, 0
	global_load_lds_dwordx4 v2, s[54:55]
	s_barrier
	s_waitcnt lgkmcnt(0)
	s_waitcnt lgkmcnt(0)
	v_mfma_f32_16x16x32_bf16 v[60:63], v[130:133], v[156:159], v[60:63]
	v_mfma_f32_16x16x32_bf16 v[56:59], v[144:147], v[156:159], v[56:59]
	v_mfma_f32_16x16x32_bf16 v[44:47], v[130:133], v[164:167], v[44:47]
	v_mfma_f32_16x16x32_bf16 v[40:43], v[144:147], v[164:167], v[40:43]
	v_mfma_f32_16x16x32_bf16 v[28:31], v[130:133], v[184:187], v[28:31]
	v_mfma_f32_16x16x32_bf16 v[24:27], v[144:147], v[184:187], v[24:27]
	v_mfma_f32_16x16x32_bf16 v[12:15], v[130:133], v[228:231], v[12:15]
	v_mfma_f32_16x16x32_bf16 v[8:11], v[144:147], v[228:231], v[8:11]
	v_mfma_f32_16x16x32_bf16 v[60:63], v[134:137], v[160:163], v[60:63]
	v_mfma_f32_16x16x32_bf16 v[56:59], v[148:151], v[160:163], v[56:59]
	v_mfma_f32_16x16x32_bf16 v[44:47], v[134:137], v[180:183], v[44:47]
	v_mfma_f32_16x16x32_bf16 v[40:43], v[148:151], v[180:183], v[40:43]
	v_mfma_f32_16x16x32_bf16 v[28:31], v[134:137], v[224:227], v[28:31]
	v_mfma_f32_16x16x32_bf16 v[24:27], v[148:151], v[224:227], v[24:27]
	v_mfma_f32_16x16x32_bf16 v[12:15], v[134:137], v[232:235], v[12:15]
	v_mfma_f32_16x16x32_bf16 v[8:11], v[148:151], v[232:235], v[8:11]
	s_barrier
	s_add_u32 s74, s52, 0x40000
	s_addc_u32 s75, s53, 0
	s_add_i32 m0, s59, 0x14000
	s_nop 0
	global_load_lds_dwordx4 v0, s[74:75]
	s_add_i32 m0, s59, 0x16000
	s_nop 0
	global_load_lds_dwordx4 v2, s[74:75]
	s_waitcnt vmcnt(6)
	s_barrier
; #define G_STAGE(bufoff, gbase) do { _Pragma("unroll") for (int _i = 0; _i < 2; ++_i) \
;         __builtin_amdgcn_global_load_lds((const unsigned*)((const char*)(gbase) + voff[_i]), (LAS unsigned*)(lds + (bufoff) + ldsw + _i * 8192), 16, 0, 0); } while (0)
; #define G_LDA(dst, b, h) do { _Pragma("unroll") for (int m = 0; m < 4; ++m) _Pragma("unroll") for (int k = 0; k < 2; ++k) dst[m][k] = *(const LAS bf16x8*)(lds + G_SA(b, h) + aoff + m * 2048 + k * 1024); } while (0)
; #define G_LDB(dst, b, h) do { _Pragma("unroll") for (int n = 0; n < 2; ++n) _Pragma("unroll") for (int k = 0; k < 2; ++k) dst[n][k] = *(const LAS bf16x8*)(lds + G_SB(b, h) + boff + n * 2048 + k * 1024); } while (0)
; #define G_MMA(ai, bj, At, Bt) do { __builtin_amdgcn_s_setprio(1); _Pragma("unroll") for (int m = 0; m < 4; ++m) _Pragma("unroll") for (int n = 0; n < 2; ++n) _Pragma("unroll") for (int k = 0; k < 2; ++k) \
;         acc[ai][bj][m][n] = MFMA16(Bt[n][k], At[m][k], acc[ai][bj][m][n]); __builtin_amdgcn_s_setprio(0); } while (0)
; #define G_WAIT_V(n) asm volatile("s_waitcnt vmcnt(" #n ")" ::: "memory")
; #define G_WAIT_L(n) asm volatile("s_waitcnt lgkmcnt(" #n ")" ::: "memory")
; #define G_BAR __builtin_amdgcn_s_barrier()
; #define G_SCHED __builtin_amdgcn_sched_barrier(0)
; template <class Epi>
; __device__ __forceinline__ void gemm_phase(LAS unsigned char* lds, const bf16_t* Ag, const bf16_t* Btg, const int K, const int nM, const int nN, const Epi& E) {
;     ...
;             G_WAIT_V(6); G_BAR; G_MMA(1, 1, At, B1); G_BAR;
;             G_LDB(B0, 1, 0); G_SCHED; G_LDA(At, 1, 0); G_STAGE(G_SA(0, 1), a2 + hstep);
;             G_WAIT_L(8); G_BAR; G_WAIT_L(0); G_MMA(0, 0, At, B0); G_BAR; G_SCHED;
;             G_LDB(B1, 1, 1); G_STAGE(G_SB(1, 0), b3);
	v_mfma_f32_16x16x32_bf16 v[68:71], v[236:239], v[156:159], v[68:71]
	v_mfma_f32_16x16x32_bf16 v[64:67], v[244:247], v[156:159], v[64:67]
	v_mfma_f32_16x16x32_bf16 v[52:55], v[236:239], v[164:167], v[52:55]
	v_mfma_f32_16x16x32_bf16 v[48:51], v[244:247], v[164:167], v[48:51]
	v_mfma_f32_16x16x32_bf16 v[36:39], v[236:239], v[184:187], v[36:39]
	v_mfma_f32_16x16x32_bf16 v[32:35], v[244:247], v[184:187], v[32:35]
	v_mfma_f32_16x16x32_bf16 v[20:23], v[236:239], v[228:231], v[20:23]
	v_mfma_f32_16x16x32_bf16 v[16:19], v[244:247], v[228:231], v[16:19]
	v_mfma_f32_16x16x32_bf16 v[68:71], v[240:243], v[160:163], v[68:71]
	v_mfma_f32_16x16x32_bf16 v[64:67], v[248:251], v[160:163], v[64:67]
	v_mfma_f32_16x16x32_bf16 v[52:55], v[240:243], v[180:183], v[52:55]
	v_mfma_f32_16x16x32_bf16 v[48:51], v[248:251], v[180:183], v[48:51]
	v_mfma_f32_16x16x32_bf16 v[36:39], v[240:243], v[224:227], v[36:39]
	v_mfma_f32_16x16x32_bf16 v[32:35], v[248:251], v[224:227], v[32:35]
	v_mfma_f32_16x16x32_bf16 v[20:23], v[240:243], v[232:235], v[20:23]
	v_mfma_f32_16x16x32_bf16 v[16:19], v[248:251], v[232:235], v[16:19]
	s_barrier
	ds_read_b128 v[130:133], v217 offset:32768
	ds_read_b128 v[134:137], v217 offset:33792
	ds_read_b128 v[144:147], v217 offset:34816
	ds_read_b128 v[148:151], v217 offset:35840
	s_add_u32 s54, s54, 0x40000
	s_addc_u32 s55, s55, 0
	s_mov_b32 m0, s62
	ds_read_b128 v[156:159], v222 offset:32768
	ds_read_b128 v[160:163], v222 offset:33792
	ds_read_b128 v[164:167], v222 offset:34816
	ds_read_b128 v[180:183], v222 offset:35840
	ds_read_b128 v[184:187], v222 offset:36864
	ds_read_b128 v[224:227], v222 offset:37888
	ds_read_b128 v[228:231], v222 offset:38912
	global_load_lds_dwordx4 v0, s[54:55]
	s_mov_b32 m0, s63
	ds_read_b128 v[232:235], v222 offset:39936
	global_load_lds_dwordx4 v2, s[54:55]
	s_waitcnt lgkmcnt(8)
	s_barrier
	s_waitcnt lgkmcnt(0)
	s_waitcnt lgkmcnt(0)
	v_mfma_f32_16x16x32_bf16 v[152:155], v[130:133], v[156:159], v[152:155]
	v_mfma_f32_16x16x32_bf16 v[138:141], v[144:147], v[156:159], v[138:141]
	v_mfma_f32_16x16x32_bf16 v[116:119], v[130:133], v[164:167], v[116:119]
	v_mfma_f32_16x16x32_bf16 v[112:115], v[144:147], v[164:167], v[112:115]
	v_mfma_f32_16x16x32_bf16 v[100:103], v[130:133], v[184:187], v[100:103]
	v_mfma_f32_16x16x32_bf16 v[96:99], v[144:147], v[184:187], v[96:99]
	v_mfma_f32_16x16x32_bf16 v[84:87], v[130:133], v[228:231], v[84:87]
	v_mfma_f32_16x16x32_bf16 v[80:83], v[144:147], v[228:231], v[80:83]
	v_mfma_f32_16x16x32_bf16 v[152:155], v[134:137], v[160:163], v[152:155]
	v_mfma_f32_16x16x32_bf16 v[140:143], v[148:151], v[160:163], v[138:141]
	v_mfma_f32_16x16x32_bf16 v[116:119], v[134:137], v[180:183], v[116:119]
	v_mfma_f32_16x16x32_bf16 v[112:115], v[148:151], v[180:183], v[112:115]
	v_mfma_f32_16x16x32_bf16 v[100:103], v[134:137], v[224:227], v[100:103]
	v_mfma_f32_16x16x32_bf16 v[96:99], v[148:151], v[224:227], v[96:99]
	v_mfma_f32_16x16x32_bf16 v[84:87], v[134:137], v[232:235], v[84:87]
	v_mfma_f32_16x16x32_bf16 v[80:83], v[148:151], v[232:235], v[80:83]
	s_barrier
	s_add_i32 s54, 0, 0x1c000
	s_add_i32 m0, s59, 0x18000
	ds_read_b128 v[236:239], v217 offset:49152
	ds_read_b128 v[240:243], v217 offset:50176
	ds_read_b128 v[244:247], v217 offset:51200
	ds_read_b128 v[248:251], v217 offset:52224
	s_add_u32 s98, s52, 0x80
	s_addc_u32 s99, s53, 0
	global_load_lds_dwordx4 v0, s[98:99]
	s_add_i32 m0, s59, 0x1a000
	s_nop 0
	global_load_lds_dwordx4 v2, s[98:99]
	s_barrier
; #define G_STAGE(bufoff, gbase) do { _Pragma("unroll") for (int _i = 0; _i < 2; ++_i) \
;         __builtin_amdgcn_global_load_lds((const unsigned*)((const char*)(gbase) + voff[_i]), (LAS unsigned*)(lds + (bufoff) + ldsw + _i * 8192), 16, 0, 0); } while (0)
; #define G_LDA(dst, b, h) do { _Pragma("unroll") for (int m = 0; m < 4; ++m) _Pragma("unroll") for (int k = 0; k < 2; ++k) dst[m][k] = *(const LAS bf16x8*)(lds + G_SA(b, h) + aoff + m * 2048 + k * 1024); } while (0)
; #define G_LDB(dst, b, h) do { _Pragma("unroll") for (int n = 0; n < 2; ++n) _Pragma("unroll") for (int k = 0; k < 2; ++k) dst[n][k] = *(const LAS bf16x8*)(lds + G_SB(b, h) + boff + n * 2048 + k * 1024); } while (0)
; #define G_MMA(ai, bj, At, Bt) do { __builtin_amdgcn_s_setprio(1); _Pragma("unroll") for (int m = 0; m < 4; ++m) _Pragma("unroll") for (int n = 0; n < 2; ++n) _Pragma("unroll") for (int k = 0; k < 2; ++k) \
;         acc[ai][bj][m][n] = MFMA16(Bt[n][k], At[m][k], acc[ai][bj][m][n]); __builtin_amdgcn_s_setprio(0); } while (0)
; #define G_WAIT_V(n) asm volatile("s_waitcnt vmcnt(" #n ")" ::: "memory")
; #define G_WAIT_L(n) asm volatile("s_waitcnt lgkmcnt(" #n ")" ::: "memory")
; #define G_BAR __builtin_amdgcn_s_barrier()
; #define G_SCHED __builtin_amdgcn_sched_barrier(0)
; template <class Epi>
; __device__ __forceinline__ void gemm_phase(LAS unsigned char* lds, const bf16_t* Ag, const bf16_t* Btg, const int K, const int nM, const int nN, const Epi& E) {
;     ...
;             G_LDB(B1, 1, 1); G_STAGE(G_SB(1, 0), b3);
;             G_BAR; G_WAIT_L(0); G_MMA(0, 1, At, B1); G_BAR;
;             G_LDA(At, 1, 1); G_STAGE(G_SA(1, 0), a3);
;             G_BAR; G_WAIT_L(0); G_MMA(1, 0, At, B0); G_BAR; G_SCHED;
;             G_STAGE(G_SB(1, 1), b3 + hstep);
;             G_WAIT_V(6); G_BAR; G_MMA(1, 1, At, B1); G_BAR;
	s_waitcnt lgkmcnt(0)
	s_waitcnt lgkmcnt(0)
	v_mfma_f32_16x16x32_bf16 v[124:127], v[236:239], v[156:159], v[124:127]
	v_mfma_f32_16x16x32_bf16 v[120:123], v[244:247], v[156:159], v[120:123]
	v_mfma_f32_16x16x32_bf16 v[108:111], v[236:239], v[164:167], v[108:111]
	v_mfma_f32_16x16x32_bf16 v[104:107], v[244:247], v[164:167], v[104:107]
	v_mfma_f32_16x16x32_bf16 v[92:95], v[236:239], v[184:187], v[92:95]
	v_mfma_f32_16x16x32_bf16 v[88:91], v[244:247], v[184:187], v[88:91]
	v_mfma_f32_16x16x32_bf16 v[76:79], v[236:239], v[228:231], v[76:79]
	v_mfma_f32_16x16x32_bf16 v[72:75], v[244:247], v[228:231], v[72:75]
	v_mfma_f32_16x16x32_bf16 v[124:127], v[240:243], v[160:163], v[124:127]
	v_mfma_f32_16x16x32_bf16 v[120:123], v[248:251], v[160:163], v[120:123]
	v_mfma_f32_16x16x32_bf16 v[108:111], v[240:243], v[180:183], v[108:111]
	v_mfma_f32_16x16x32_bf16 v[104:107], v[248:251], v[180:183], v[104:107]
	v_mfma_f32_16x16x32_bf16 v[92:95], v[240:243], v[224:227], v[92:95]
	v_mfma_f32_16x16x32_bf16 v[88:91], v[248:251], v[224:227], v[88:91]
	v_mfma_f32_16x16x32_bf16 v[76:79], v[240:243], v[232:235], v[76:79]
	v_mfma_f32_16x16x32_bf16 v[72:75], v[248:251], v[232:235], v[72:75]
	s_mov_b32 m0, s64
	s_barrier
	ds_read_b128 v[156:159], v222 offset:49152
	ds_read_b128 v[160:163], v222 offset:50176
	ds_read_b128 v[164:167], v222 offset:51200
	ds_read_b128 v[180:183], v222 offset:52224
	ds_read_b128 v[184:187], v222 offset:53248
	ds_read_b128 v[224:227], v222 offset:54272
	ds_read_b128 v[228:231], v222 offset:55296
	global_load_lds_dwordx4 v0, s[76:77]
	s_mov_b32 m0, s65
	ds_read_b128 v[232:235], v222 offset:56320
	global_load_lds_dwordx4 v2, s[76:77]
	s_barrier
	s_waitcnt lgkmcnt(0)
	s_waitcnt lgkmcnt(0)
	v_mfma_f32_16x16x32_bf16 v[60:63], v[130:133], v[156:159], v[60:63]
	v_mfma_f32_16x16x32_bf16 v[56:59], v[144:147], v[156:159], v[56:59]
	v_mfma_f32_16x16x32_bf16 v[44:47], v[130:133], v[164:167], v[44:47]
	v_mfma_f32_16x16x32_bf16 v[40:43], v[144:147], v[164:167], v[40:43]
	v_mfma_f32_16x16x32_bf16 v[28:31], v[130:133], v[184:187], v[28:31]
	v_mfma_f32_16x16x32_bf16 v[24:27], v[144:147], v[184:187], v[24:27]
	v_mfma_f32_16x16x32_bf16 v[12:15], v[130:133], v[228:231], v[12:15]
	v_mfma_f32_16x16x32_bf16 v[8:11], v[144:147], v[228:231], v[8:11]
	v_mfma_f32_16x16x32_bf16 v[60:63], v[134:137], v[160:163], v[60:63]
	v_mfma_f32_16x16x32_bf16 v[56:59], v[148:151], v[160:163], v[56:59]
	v_mfma_f32_16x16x32_bf16 v[44:47], v[134:137], v[180:183], v[44:47]
	v_mfma_f32_16x16x32_bf16 v[40:43], v[148:151], v[180:183], v[40:43]
	v_mfma_f32_16x16x32_bf16 v[28:31], v[134:137], v[224:227], v[28:31]
	v_mfma_f32_16x16x32_bf16 v[24:27], v[148:151], v[224:227], v[24:27]
	v_mfma_f32_16x16x32_bf16 v[12:15], v[134:137], v[232:235], v[12:15]
	v_mfma_f32_16x16x32_bf16 v[8:11], v[148:151], v[232:235], v[8:11]
	s_barrier
	s_add_u32 s52, s52, 0x40080
	s_addc_u32 s53, s53, 0
	s_add_i32 s26, s54, s59
	s_add_i32 m0, s59, 0x1c000
	s_nop 0
	global_load_lds_dwordx4 v0, s[52:53]
	s_add_i32 m0, s59, 0x1e000
	s_nop 0
	global_load_lds_dwordx4 v2, s[52:53]
	s_waitcnt vmcnt(6)
	s_barrier
	v_mfma_f32_16x16x32_bf16 v[68:71], v[236:239], v[156:159], v[68:71]
	v_mfma_f32_16x16x32_bf16 v[64:67], v[244:247], v[156:159], v[64:67]
	v_mfma_f32_16x16x32_bf16 v[52:55], v[236:239], v[164:167], v[52:55]
	v_mfma_f32_16x16x32_bf16 v[48:51], v[244:247], v[164:167], v[48:51]
	v_mfma_f32_16x16x32_bf16 v[36:39], v[236:239], v[184:187], v[36:39]
	v_mfma_f32_16x16x32_bf16 v[32:35], v[244:247], v[184:187], v[32:35]
	v_mfma_f32_16x16x32_bf16 v[20:23], v[236:239], v[228:231], v[20:23]
	v_mfma_f32_16x16x32_bf16 v[16:19], v[244:247], v[228:231], v[16:19]
	v_mfma_f32_16x16x32_bf16 v[68:71], v[240:243], v[160:163], v[68:71]
	v_mfma_f32_16x16x32_bf16 v[64:67], v[248:251], v[160:163], v[64:67]
	v_mfma_f32_16x16x32_bf16 v[52:55], v[240:243], v[180:183], v[52:55]
	v_mfma_f32_16x16x32_bf16 v[48:51], v[248:251], v[180:183], v[48:51]
	v_mfma_f32_16x16x32_bf16 v[36:39], v[240:243], v[224:227], v[36:39]
	v_mfma_f32_16x16x32_bf16 v[32:35], v[248:251], v[224:227], v[32:35]
	v_mfma_f32_16x16x32_bf16 v[20:23], v[240:243], v[232:235], v[20:23]
	v_mfma_f32_16x16x32_bf16 v[16:19], v[248:251], v[232:235], v[16:19]
	s_add_i32 s72, s72, 2
	s_add_u32 s70, s70, 0x100
	s_addc_u32 s71, s71, 0
	s_add_u32 s50, s50, 0x100
	s_addc_u32 s51, s51, 0
	s_cmp_gt_u32 s72, 13
	s_barrier
	s_cbranch_scc1 .LBB0_852
